# phase 8 epilogue: eight row-statistic loads hoisted and issued together; K staging with all 16 loads in flight
# baseline (speedup 1.0000x reference)
; #define LAS __attribute__((address_space(3)))
; __device__ __forceinline__ unsigned pk2(float lo, float hi) { return pg8::cvt_pk_bf16(lo, hi); }
; __device__ __forceinline__ float row_rs(const float* ssq, int row) { return ssq ? rsqrtf(ssq[row] * (1.f / 1024.f) + RMS_EPS) : 1.f; }
;     __device__ __forceinline__ void fused(f32x4 (&acc)[2][2][4][2], const pg8::Unit& u, int wr, int wc, int fr, int fq, LAS unsigned char* lds, int wid, int lane) const {
;     ...
;             for (int m = 0; m < 4; ++m) { const int rl = ai * 128 + wr * 64 + m * 16 + fr; const float rs = pg8::row_rs(ssq, u.pm * 256 + rl);
; #pragma unroll
;                 for (int bj = 0; bj < 2; ++bj)
; #pragma unroll
;                     for (int n = 0; n < 2; ++n) { const f32x4 v = acc[ai][bj][m][n] * rs; v2u w; w.x = pk2(v[0], v[1]); w.y = pk2(v[2], v[3]);
;                         *(LAS v2u*)(QI + rl * XP + bj * 128 + wc * 32 + n * 16 + 4 * fq) = w; } }
.LBB0_1108:
	s_add_u32 s4, s48, 0x20000
	s_addc_u32 s5, s49, 0
	v_lshrrev_b32_e32 v128, 5, v208
	s_lshl_b32 s13, s10, 8
	v_lshlrev_b32_e32 v189, 4, v128
	v_lshlrev_b32_e32 v211, 2, v128
	v_add_u32_e32 v128, s13, v146
	v_ashrrev_i32_e32 v129, 31, v128
	v_lshl_add_u64 v[132:133], v[128:129], 2, s[4:5]
	s_barrier
	global_load_dword v131, v[132:133], off
	global_load_dword v136, v[132:133], off offset:64
	global_load_dword v137, v[132:133], off offset:128
	global_load_dword v138, v[132:133], off offset:192
	global_load_dword v139, v[132:133], off offset:512
	global_load_dword v140, v[132:133], off offset:576
	global_load_dword v141, v[132:133], off offset:640
	global_load_dword v142, v[132:133], off offset:704
	s_lshl_b32 s6, s39, 6
	v_mov_b32_e32 v129, 0x358637bd
	s_add_i32 s7, s6, 0
	s_mov_b32 s6, 0x800000
	s_movk_i32 s14, 0x210
	s_ashr_i32 s15, s10, 4
	s_add_i32 s12, 0, 0x10800
	s_andn2_b32 s30, s30, 63
	v_and_b32_e32 v210, 31, v209
	v_and_b32_e32 v188, 8, v147
	v_and_b32_e32 v190, 0x1f0, v144
	v_lshl_or_b32 v214, s31, 5, v210
	v_mov_b32_e32 v191, 0
	v_lshlrev_b32_e32 v130, 1, v188
	v_add_u32_e32 v216, 0, v190
	v_add_u32_e32 v215, s12, v190
	v_mul_u32_u24_e32 v212, 0x210, v210
	v_add3_u32 v213, 0, v212, v189
	s_mov_b32 s11, 0
	s_waitcnt vmcnt(0)
	v_fmamk_f32 v131, v131, 0x3a800000, v129
	v_cmp_gt_f32_e32 vcc, s6, v131
	v_mul_f32_e32 v132, 0x4b800000, v131
	s_nop 0
	v_cndmask_b32_e32 v131, v131, v132, vcc
	v_rsq_f32_e32 v131, v131
	s_nop 0
	v_mul_f32_e32 v132, 0x45800000, v131
	v_cndmask_b32_e32 v132, v131, v132, vcc
	v_mul_lo_u32 v131, v146, s14
	v_pk_mul_f32 v[118:119], v[118:119], v[132:133] op_sel_hi:[1,0]
	v_pk_mul_f32 v[116:117], v[116:117], v[132:133] op_sel_hi:[1,0]
	v_pk_mul_f32 v[114:115], v[114:115], v[132:133] op_sel_hi:[1,0]
	v_pk_mul_f32 v[112:113], v[112:113], v[132:133] op_sel_hi:[1,0]
	v_add3_u32 v131, s7, v145, v131
	v_cvt_pk_bf16_f32 v116, v116, v117
	v_cvt_pk_bf16_f32 v117, v118, v119
	v_cvt_pk_bf16_f32 v112, v112, v113
	v_cvt_pk_bf16_f32 v113, v114, v115
	ds_write2_b64 v131, v[116:117], v[112:113] offset0:32 offset1:36
	v_pk_mul_f32 v[126:127], v[126:127], v[132:133] op_sel_hi:[1,0]
	v_pk_mul_f32 v[124:125], v[124:125], v[132:133] op_sel_hi:[1,0]
	v_pk_mul_f32 v[122:123], v[122:123], v[132:133] op_sel_hi:[1,0]
	v_pk_mul_f32 v[120:121], v[120:121], v[132:133] op_sel_hi:[1,0]
	v_cvt_pk_bf16_f32 v124, v124, v125
	v_cvt_pk_bf16_f32 v125, v126, v127
	v_cvt_pk_bf16_f32 v120, v120, v121
	v_cvt_pk_bf16_f32 v121, v122, v123
	ds_write2_b64 v131, v[124:125], v[120:121] offset1:4
	s_waitcnt vmcnt(0)
	v_fmamk_f32 v112, v136, 0x3a800000, v129
	v_cmp_gt_f32_e32 vcc, s6, v112
	v_mul_f32_e32 v113, 0x4b800000, v112
	s_nop 0
	v_cndmask_b32_e32 v112, v112, v113, vcc
	v_rsq_f32_e32 v112, v112
	s_nop 0
	v_mul_f32_e32 v113, 0x45800000, v112
	v_cndmask_b32_e32 v112, v112, v113, vcc
	v_add_u32_e32 v113, 0x2100, v131
	v_pk_mul_f32 v[106:107], v[106:107], v[112:113] op_sel_hi:[1,0]
	v_pk_mul_f32 v[104:105], v[104:105], v[112:113] op_sel_hi:[1,0]
	v_pk_mul_f32 v[102:103], v[102:103], v[112:113] op_sel_hi:[1,0]
	v_pk_mul_f32 v[100:101], v[100:101], v[112:113] op_sel_hi:[1,0]
	v_pk_mul_f32 v[98:99], v[98:99], v[112:113] op_sel_hi:[1,0]
	v_pk_mul_f32 v[96:97], v[96:97], v[112:113] op_sel_hi:[1,0]
	v_cvt_pk_bf16_f32 v104, v104, v105
	v_cvt_pk_bf16_f32 v105, v106, v107
	v_add_u32_e32 v106, 0x2000, v131
	v_cvt_pk_bf16_f32 v100, v100, v101
	v_cvt_pk_bf16_f32 v101, v102, v103
	v_cvt_pk_bf16_f32 v96, v96, v97
	v_cvt_pk_bf16_f32 v97, v98, v99
	ds_write2_b64 v106, v[100:101], v[96:97] offset0:64 offset1:68
	v_pk_mul_f32 v[110:111], v[110:111], v[112:113] op_sel_hi:[1,0]
	v_pk_mul_f32 v[108:109], v[108:109], v[112:113] op_sel_hi:[1,0]
	s_waitcnt vmcnt(0)
	v_fmamk_f32 v96, v137, 0x3a800000, v129
	v_cmp_gt_f32_e32 vcc, s6, v96
	v_mul_f32_e32 v97, 0x4b800000, v96
	v_cvt_pk_bf16_f32 v108, v108, v109
	v_cndmask_b32_e32 v96, v96, v97, vcc
	v_rsq_f32_e32 v96, v96
	v_cvt_pk_bf16_f32 v109, v110, v111
	ds_write2_b64 v106, v[108:109], v[104:105] offset0:32 offset1:36
	v_mul_f32_e32 v97, 0x45800000, v96
	v_cndmask_b32_e32 v96, v96, v97, vcc
	v_add_u32_e32 v97, 0x4200, v131
	v_pk_mul_f32 v[90:91], v[90:91], v[96:97] op_sel_hi:[1,0]
	v_pk_mul_f32 v[88:89], v[88:89], v[96:97] op_sel_hi:[1,0]
	v_pk_mul_f32 v[86:87], v[86:87], v[96:97] op_sel_hi:[1,0]
	v_pk_mul_f32 v[84:85], v[84:85], v[96:97] op_sel_hi:[1,0]
	v_pk_mul_f32 v[82:83], v[82:83], v[96:97] op_sel_hi:[1,0]
	v_pk_mul_f32 v[80:81], v[80:81], v[96:97] op_sel_hi:[1,0]
	v_cvt_pk_bf16_f32 v88, v88, v89
	v_cvt_pk_bf16_f32 v89, v90, v91
	v_add_u32_e32 v90, 0x4000, v131
	v_cvt_pk_bf16_f32 v84, v84, v85
	v_cvt_pk_bf16_f32 v85, v86, v87
	v_cvt_pk_bf16_f32 v80, v80, v81
	v_cvt_pk_bf16_f32 v81, v82, v83
	ds_write2_b64 v90, v[84:85], v[80:81] offset0:96 offset1:100
	v_pk_mul_f32 v[94:95], v[94:95], v[96:97] op_sel_hi:[1,0]
	v_pk_mul_f32 v[92:93], v[92:93], v[96:97] op_sel_hi:[1,0]
	s_waitcnt vmcnt(0)
	v_fmamk_f32 v80, v138, 0x3a800000, v129
	v_cmp_gt_f32_e32 vcc, s6, v80
	v_mul_f32_e32 v81, 0x4b800000, v80
	v_cvt_pk_bf16_f32 v92, v92, v93
	v_cndmask_b32_e32 v80, v80, v81, vcc
	v_rsq_f32_e32 v80, v80
	v_cvt_pk_bf16_f32 v93, v94, v95
	ds_write2_b64 v90, v[92:93], v[88:89] offset0:64 offset1:68
	v_mul_f32_e32 v81, 0x45800000, v80
	v_cndmask_b32_e32 v82, v80, v81, vcc
	v_pk_mul_f32 v[74:75], v[74:75], v[82:83] op_sel_hi:[1,0]
	v_pk_mul_f32 v[72:73], v[72:73], v[82:83] op_sel_hi:[1,0]
	v_pk_mul_f32 v[70:71], v[70:71], v[82:83] op_sel_hi:[1,0]
	v_pk_mul_f32 v[68:69], v[68:69], v[82:83] op_sel_hi:[1,0]
	v_pk_mul_f32 v[66:67], v[66:67], v[82:83] op_sel_hi:[1,0]
	v_pk_mul_f32 v[64:65], v[64:65], v[82:83] op_sel_hi:[1,0]
	v_cvt_pk_bf16_f32 v72, v72, v73
	v_cvt_pk_bf16_f32 v73, v74, v75
	v_add_u32_e32 v74, 0x6000, v131
	v_cvt_pk_bf16_f32 v68, v68, v69
	v_cvt_pk_bf16_f32 v69, v70, v71
	v_cvt_pk_bf16_f32 v64, v64, v65
	v_cvt_pk_bf16_f32 v65, v66, v67
	ds_write2_b64 v74, v[68:69], v[64:65] offset0:128 offset1:132
	v_add_u32_e32 v80, 0x6300, v131
	v_pk_mul_f32 v[78:79], v[78:79], v[82:83] op_sel_hi:[1,0]
	v_pk_mul_f32 v[76:77], v[76:77], v[82:83] op_sel_hi:[1,0]
	v_add3_u32 v68, s12, v212, v189
	v_cvt_pk_bf16_f32 v76, v76, v77
	v_cvt_pk_bf16_f32 v77, v78, v79
	ds_write2_b64 v74, v[76:77], v[72:73] offset0:96 offset1:100
	v_add3_u32 v189, s12, v189, v212
	s_waitcnt vmcnt(0)
; __device__ __forceinline__ float row_rs(const float* ssq, int row) { return ssq ? rsqrtf(ssq[row] * (1.f / 1024.f) + RMS_EPS) : 1.f; }
; #define LAS __attribute__((address_space(3)))
; __device__ __forceinline__ unsigned pk2(float lo, float hi) { return pg8::cvt_pk_bf16(lo, hi); }
;     __device__ __forceinline__ void fused(f32x4 (&acc)[2][2][4][2], const pg8::Unit& u, int wr, int wc, int fr, int fq, LAS unsigned char* lds, int wid, int lane) const {
;     ...
;             for (int m = 0; m < 4; ++m) { const int rl = ai * 128 + wr * 64 + m * 16 + fr; const float rs = pg8::row_rs(ssq, u.pm * 256 + rl);
; #pragma unroll
;                 for (int bj = 0; bj < 2; ++bj)
; #pragma unroll
;                     for (int n = 0; n < 2; ++n) { const f32x4 v = acc[ai][bj][m][n] * rs; v2u w; w.x = pk2(v[0], v[1]); w.y = pk2(v[2], v[3]);
;                         *(LAS v2u*)(QI + rl * XP + bj * 128 + wc * 32 + n * 16 + 4 * fq) = w; } }
;         __syncthreads();
	v_fmamk_f32 v64, v139, 0x3a800000, v129
	v_cmp_gt_f32_e32 vcc, s6, v64
	v_mul_f32_e32 v65, 0x4b800000, v64
	s_nop 0
	v_cndmask_b32_e32 v64, v64, v65, vcc
	v_rsq_f32_e32 v64, v64
	s_nop 0
	v_mul_f32_e32 v65, 0x45800000, v64
	v_cndmask_b32_e32 v66, v64, v65, vcc
	v_pk_mul_f32 v[54:55], v[54:55], v[66:67] op_sel_hi:[1,0]
	v_pk_mul_f32 v[52:53], v[52:53], v[66:67] op_sel_hi:[1,0]
	v_pk_mul_f32 v[50:51], v[50:51], v[66:67] op_sel_hi:[1,0]
	v_pk_mul_f32 v[48:49], v[48:49], v[66:67] op_sel_hi:[1,0]
	v_cvt_pk_bf16_f32 v52, v52, v53
	v_cvt_pk_bf16_f32 v53, v54, v55
	v_cvt_pk_bf16_f32 v48, v48, v49
	v_cvt_pk_bf16_f32 v49, v50, v51
	v_add_u32_e32 v50, 0xe800, v113
	ds_write2_b64 v50, v[52:53], v[48:49] offset1:4
	v_pk_mul_f32 v[62:63], v[62:63], v[66:67] op_sel_hi:[1,0]
	v_pk_mul_f32 v[60:61], v[60:61], v[66:67] op_sel_hi:[1,0]
	v_pk_mul_f32 v[58:59], v[58:59], v[66:67] op_sel_hi:[1,0]
	v_pk_mul_f32 v[56:57], v[56:57], v[66:67] op_sel_hi:[1,0]
	v_cvt_pk_bf16_f32 v60, v60, v61
	v_cvt_pk_bf16_f32 v61, v62, v63
	v_cvt_pk_bf16_f32 v56, v56, v57
	v_cvt_pk_bf16_f32 v57, v58, v59
	v_add_u32_e32 v58, 0xe000, v113
	ds_write2_b64 v58, v[60:61], v[56:57] offset0:224 offset1:228
	v_add_u32_e32 v64, 0xe700, v113
	s_waitcnt vmcnt(0)
	v_fmamk_f32 v48, v140, 0x3a800000, v129
	v_cmp_gt_f32_e32 vcc, s6, v48
	v_mul_f32_e32 v49, 0x4b800000, v48
	s_nop 0
	v_cndmask_b32_e32 v48, v48, v49, vcc
	v_rsq_f32_e32 v48, v48
	s_nop 0
	v_mul_f32_e32 v49, 0x45800000, v48
	v_cndmask_b32_e32 v48, v48, v49, vcc
	v_pk_mul_f32 v[38:39], v[38:39], v[48:49] op_sel_hi:[1,0]
	v_pk_mul_f32 v[36:37], v[36:37], v[48:49] op_sel_hi:[1,0]
	v_pk_mul_f32 v[34:35], v[34:35], v[48:49] op_sel_hi:[1,0]
	v_pk_mul_f32 v[32:33], v[32:33], v[48:49] op_sel_hi:[1,0]
	v_cvt_pk_bf16_f32 v36, v36, v37
	v_cvt_pk_bf16_f32 v37, v38, v39
	v_cvt_pk_bf16_f32 v32, v32, v33
	v_cvt_pk_bf16_f32 v33, v34, v35
	v_add_u32_e32 v34, 0xe800, v97
	ds_write2_b64 v34, v[36:37], v[32:33] offset1:4
	v_pk_mul_f32 v[46:47], v[46:47], v[48:49] op_sel_hi:[1,0]
	v_pk_mul_f32 v[44:45], v[44:45], v[48:49] op_sel_hi:[1,0]
	v_pk_mul_f32 v[42:43], v[42:43], v[48:49] op_sel_hi:[1,0]
	v_pk_mul_f32 v[40:41], v[40:41], v[48:49] op_sel_hi:[1,0]
	v_cvt_pk_bf16_f32 v44, v44, v45
	v_cvt_pk_bf16_f32 v45, v46, v47
	v_cvt_pk_bf16_f32 v40, v40, v41
	v_cvt_pk_bf16_f32 v41, v42, v43
	v_add_u32_e32 v42, 0xe000, v97
	ds_write2_b64 v42, v[44:45], v[40:41] offset0:224 offset1:228
	s_waitcnt vmcnt(0)
	v_fmamk_f32 v32, v141, 0x3a800000, v129
	v_cmp_gt_f32_e32 vcc, s6, v32
	v_mul_f32_e32 v33, 0x4b800000, v32
	s_nop 0
	v_cndmask_b32_e32 v32, v32, v33, vcc
	v_rsq_f32_e32 v32, v32
	s_nop 0
	v_mul_f32_e32 v33, 0x45800000, v32
	v_cndmask_b32_e32 v32, v32, v33, vcc
	v_pk_mul_f32 v[22:23], v[22:23], v[32:33] op_sel_hi:[1,0]
	v_pk_mul_f32 v[20:21], v[20:21], v[32:33] op_sel_hi:[1,0]
	v_pk_mul_f32 v[18:19], v[18:19], v[32:33] op_sel_hi:[1,0]
	v_pk_mul_f32 v[16:17], v[16:17], v[32:33] op_sel_hi:[1,0]
	v_cvt_pk_bf16_f32 v20, v20, v21
	v_cvt_pk_bf16_f32 v21, v22, v23
	v_cvt_pk_bf16_f32 v16, v16, v17
	v_cvt_pk_bf16_f32 v17, v18, v19
	v_add_u32_e32 v18, 0xe800, v80
	ds_write2_b64 v18, v[20:21], v[16:17] offset1:4
	v_pk_mul_f32 v[30:31], v[30:31], v[32:33] op_sel_hi:[1,0]
	v_pk_mul_f32 v[28:29], v[28:29], v[32:33] op_sel_hi:[1,0]
	v_pk_mul_f32 v[26:27], v[26:27], v[32:33] op_sel_hi:[1,0]
	v_pk_mul_f32 v[24:25], v[24:25], v[32:33] op_sel_hi:[1,0]
	v_cvt_pk_bf16_f32 v28, v28, v29
	v_cvt_pk_bf16_f32 v29, v30, v31
	v_cvt_pk_bf16_f32 v24, v24, v25
	v_cvt_pk_bf16_f32 v25, v26, v27
	v_add_u32_e32 v26, 0xe000, v80
	v_or_b32_e32 v30, s30, v208
	ds_write2_b64 v26, v[28:29], v[24:25] offset0:224 offset1:228
	v_ashrrev_i32_e32 v34, 5, v30
	v_add_u32_e32 v20, 0xa00, v30
	v_add_u32_e32 v24, 0xc00, v30
	v_ashrrev_i32_e32 v44, 5, v20
	v_ashrrev_i32_e32 v46, 5, v24
	v_ashrrev_i32_e32 v35, 31, v34
	v_ashrrev_i32_e32 v45, 31, v44
	v_ashrrev_i32_e32 v47, 31, v46
	v_lshlrev_b64 v[192:193], 11, v[34:35]
	v_lshlrev_b64 v[202:203], 11, v[44:45]
	v_lshlrev_b64 v[204:205], 11, v[46:47]
	v_mul_lo_u32 v34, v34, s14
	v_add_u32_e32 v223, v216, v34
	v_add_u32_e32 v230, v215, v34
	s_waitcnt vmcnt(0)
	v_fmac_f32_e32 v129, 0x3a800000, v142
	v_cmp_gt_f32_e32 vcc, s6, v129
	v_mul_f32_e32 v16, 0x4b800000, v129
	s_lshl_b32 s6, s15, 8
	v_cndmask_b32_e32 v16, v129, v16, vcc
	v_rsq_f32_e32 v16, v16
	s_ashr_i32 s7, s6, 31
	s_lshl_b64 s[4:5], s[6:7], 11
	s_add_u32 s10, s48, s4
	v_mul_f32_e32 v17, 0x45800000, v16
	v_cndmask_b32_e32 v16, v16, v17, vcc
	s_addc_u32 s19, s49, s5
	s_lshl_b32 s16, s34, 8
	v_pk_mul_f32 v[14:15], v[14:15], v[16:17] op_sel_hi:[1,0]
	v_pk_mul_f32 v[12:13], v[12:13], v[16:17] op_sel_hi:[1,0]
	v_pk_mul_f32 v[10:11], v[10:11], v[16:17] op_sel_hi:[1,0]
	v_pk_mul_f32 v[8:9], v[8:9], v[16:17] op_sel_hi:[1,0]
	v_pk_mul_f32 v[6:7], v[6:7], v[16:17] op_sel_hi:[1,0]
	v_pk_mul_f32 v[4:5], v[4:5], v[16:17] op_sel_hi:[1,0]
	v_pk_mul_f32 v[2:3], v[2:3], v[16:17] op_sel_hi:[1,0]
	v_pk_mul_f32 v[0:1], v[0:1], v[16:17] op_sel_hi:[1,0]
	s_ashr_i32 s17, s16, 31
	v_cvt_pk_bf16_f32 v12, v12, v13
	v_cvt_pk_bf16_f32 v13, v14, v15
	v_cvt_pk_bf16_f32 v8, v8, v9
	v_cvt_pk_bf16_f32 v9, v10, v11
	v_add_u32_e32 v10, 0x6000, v64
	v_cvt_pk_bf16_f32 v4, v4, v5
	v_cvt_pk_bf16_f32 v5, v6, v7
	v_cvt_pk_bf16_f32 v0, v0, v1
	v_cvt_pk_bf16_f32 v1, v2, v3
	s_lshl_b64 s[4:5], s[16:17], 1
	ds_write2_b64 v10, v[12:13], v[8:9] offset0:96 offset1:100
	ds_write2_b64 v10, v[4:5], v[0:1] offset0:128 offset1:132
	s_add_u32 s18, s10, s4
	v_add_u32_e32 v4, 0x200, v30
	v_add_u32_e32 v8, 0x400, v30
	v_add_u32_e32 v12, 0x600, v30
	v_add_u32_e32 v16, 0x800, v30
	v_add_u32_e32 v30, 0xe00, v30
	s_addc_u32 s19, s19, s5
	v_ashrrev_i32_e32 v36, 5, v4
	v_ashrrev_i32_e32 v38, 5, v8
	v_ashrrev_i32_e32 v40, 5, v12
	v_ashrrev_i32_e32 v42, 5, v16
	v_ashrrev_i32_e32 v48, 5, v30
	v_mul_lo_u32 v0, v214, s14
	v_lshl_add_u64 v[32:33], s[18:19], 0, v[190:191]
	s_mov_b64 s[18:19], 0x5600000
	v_ashrrev_i32_e32 v37, 31, v36
	v_ashrrev_i32_e32 v39, 31, v38
	v_ashrrev_i32_e32 v41, 31, v40
	v_ashrrev_i32_e32 v43, 31, v42
	v_ashrrev_i32_e32 v49, 31, v48
	v_add3_u32 v0, 0, v130, v0
	v_lshl_add_u64 v[28:29], v[32:33], 0, s[18:19]
	v_lshlrev_b64 v[194:195], 11, v[36:37]
	v_lshlrev_b64 v[196:197], 11, v[38:39]
	v_lshlrev_b64 v[198:199], 11, v[40:41]
	v_lshlrev_b64 v[200:201], 11, v[42:43]
	v_lshlrev_b64 v[206:207], 11, v[48:49]
	s_waitcnt lgkmcnt(0)
	s_barrier
; #define LAS __attribute__((address_space(3)))
; __device__ __forceinline__ void stage_half(const bf16* g, LAS bf16* dst, int tid) {
;     v4u t[8];
; #pragma unroll
;     for (int i = 0; i < 8; ++i) { const int ch = tid + i * NT, r = ch >> 5, cc = ch & 31; t[i] = *(const v4u*)(g + (size_t)r * 1024 + cc * 8); }
; #pragma unroll
;     for (int i = 0; i < 8; ++i) { const int ch = tid + i * NT, r = ch >> 5, cc = ch & 31; *(LAS v4u*)(dst + r * XP + cc * 8) = t[i]; }
; }
; __device__ __forceinline__ void xattn_core(unsigned char* ws, LAS unsigned char* lds, int b, int hd, int qb, int tid, const bf16x8 (&qf)[16]) {
;     const int lane = tid & 63, wave = tid >> 6, r32 = lane & 31, hh = lane >> 5;
;     LAS bf16* L0 = (LAS bf16*)lds; LAS bf16* L1 = L0 + 128 * XP;
;     const bf16* Kg = (const bf16*)(ws + WS_KB) + (size_t)(b * 256) * 1024 + hd * 256;
;     const bf16* Vg = (const bf16*)(ws + WS_VT) + (size_t)(hd * 256) * 1024 + b * 256;
;     stage_half(Kg, L0, tid); stage_half(Kg + (size_t)128 * 1024, L1, tid);
;     const int q0 = b * SEQ + qb * 256 + 32 * wave;
;     __syncthreads();
;     f32x16 sacc[8];
; #pragma unroll
;     for (int mt = 0; mt < 8; ++mt) {
; #pragma unroll
;         for (int r = 0; r < 16; ++r) sacc[mt][r] = 0.f;
;         const LAS bf16* kp = (mt < 4 ? L0 : L1) + ((mt & 3) * 32 + r32) * XP + 8 * hh;
; #pragma unroll
;         for (int ds = 0; ds < 16; ++ds) { const bf16x8 kf = *(const LAS bf16x8*)(kp + 16 * ds); sacc[mt] = __builtin_amdgcn_mfma_f32_32x32x16_bf16(kf, qf[ds], sacc[mt], 0, 0, 0); } }
;     __device__ __forceinline__ void fused(f32x4 (&acc)[2][2][4][2], const pg8::Unit& u, int wr, int wc, int fr, int fq, LAS unsigned char* lds, int wid, int lane) const {
;     ...
;         const int r32 = lane & 31, hh = lane >> 5; bf16x8 qf[16];
; #pragma unroll
;         for (int ds = 0; ds < 16; ++ds) qf[ds] = *(const LAS bf16x8*)(QI + (32 * wid + r32) * XP + 16 * ds + 8 * hh);
;         __syncthreads();
	ds_read_b128 v[112:115], v0
	ds_read_b128 v[184:187], v0 offset:32
	ds_read_b128 v[180:183], v0 offset:64
	ds_read_b128 v[176:179], v0 offset:96
	ds_read_b128 v[172:175], v0 offset:128
	ds_read_b128 v[168:171], v0 offset:160
	ds_read_b128 v[164:167], v0 offset:192
	ds_read_b128 v[160:163], v0 offset:224
	ds_read_b128 v[156:159], v0 offset:256
	ds_read_b128 v[152:155], v0 offset:288
	ds_read_b128 v[148:151], v0 offset:320
	ds_read_b128 v[144:147], v0 offset:352
	ds_read_b128 v[140:143], v0 offset:384
	ds_read_b128 v[136:139], v0 offset:416
	ds_read_b128 v[132:135], v0 offset:448
	ds_read_b128 v[128:131], v0 offset:480
	v_lshl_add_u64 v[0:1], v[28:29], 0, v[192:193]
	v_lshl_add_u64 v[4:5], v[28:29], 0, v[194:195]
	v_lshl_add_u64 v[8:9], v[28:29], 0, v[196:197]
	v_lshl_add_u64 v[12:13], v[28:29], 0, v[198:199]
	v_lshl_add_u64 v[16:17], v[28:29], 0, v[200:201]
	v_lshl_add_u64 v[20:21], v[28:29], 0, v[202:203]
	v_lshl_add_u64 v[24:25], v[28:29], 0, v[204:205]
	v_lshl_add_u64 v[28:29], v[28:29], 0, v[206:207]
	s_waitcnt lgkmcnt(0)
	s_barrier
	s_mov_b64 s[18:19], 0x5640000
	v_lshl_add_u64 v[100:101], v[32:33], 0, s[18:19]
	v_lshl_add_u64 v[72:73], v[100:101], 0, v[192:193]
	v_lshl_add_u64 v[76:77], v[100:101], 0, v[194:195]
	v_lshl_add_u64 v[80:81], v[100:101], 0, v[196:197]
	v_lshl_add_u64 v[84:85], v[100:101], 0, v[198:199]
	v_lshl_add_u64 v[88:89], v[100:101], 0, v[200:201]
	v_lshl_add_u64 v[92:93], v[100:101], 0, v[202:203]
	v_lshl_add_u64 v[96:97], v[100:101], 0, v[204:205]
	v_lshl_add_u64 v[100:101], v[100:101], 0, v[206:207]
	global_load_dwordx4 v[0:3], v[0:1], off
	v_mul_lo_u32 v35, v36, s14
	global_load_dwordx4 v[4:7], v[4:5], off
	v_mul_lo_u32 v36, v38, s14
	global_load_dwordx4 v[8:11], v[8:9], off
	v_mul_lo_u32 v37, v40, s14
	global_load_dwordx4 v[12:15], v[12:13], off
	v_mul_lo_u32 v38, v42, s14
	global_load_dwordx4 v[16:19], v[16:17], off
	v_mul_lo_u32 v39, v44, s14
	global_load_dwordx4 v[20:23], v[20:21], off
	v_mul_lo_u32 v40, v46, s14
	global_load_dwordx4 v[24:27], v[24:25], off
	v_mul_lo_u32 v41, v48, s14
	global_load_dwordx4 v[28:31], v[28:29], off
	global_load_dwordx4 v[72:75], v[72:73], off
	global_load_dwordx4 v[76:79], v[76:77], off
	global_load_dwordx4 v[80:83], v[80:81], off
	global_load_dwordx4 v[84:87], v[84:85], off
	global_load_dwordx4 v[88:91], v[88:89], off
	global_load_dwordx4 v[92:95], v[92:93], off
	global_load_dwordx4 v[96:99], v[96:97], off
	global_load_dwordx4 v[100:103], v[100:101], off
	v_add_u32_e32 v222, v216, v35
	v_add_u32_e32 v221, v216, v36
	v_add_u32_e32 v220, v216, v37
	v_add_u32_e32 v219, v216, v38
	v_add_u32_e32 v218, v216, v39
	v_add_u32_e32 v217, v216, v40
	v_add_u32_e32 v216, v216, v41
	s_mov_b64 s[18:19], 0x5640000
	v_add_u32_e32 v224, v215, v35
	v_add_u32_e32 v225, v215, v36
	v_add_u32_e32 v226, v215, v37
	v_add_u32_e32 v227, v215, v38
	v_add_u32_e32 v228, v215, v39
	v_add_u32_e32 v229, v215, v40
	v_add_u32_e32 v215, v215, v41
	s_lshl_b64 s[16:17], s[16:17], 11
	s_add_u32 s16, s48, s16
	s_addc_u32 s17, s49, s17
	s_and_b32 s10, s13, 0xf00
	s_lshl_b64 s[6:7], s[6:7], 1
	s_add_u32 s16, s16, s6
	s_addc_u32 s17, s17, s7
	s_lshl_b32 s6, s15, 12
	s_mov_b64 s[14:15], 0x5800000
	s_mov_b32 s7, 0xff61b1e6
	s_or_b32 s6, s10, s6
	s_waitcnt vmcnt(15)
	ds_write_b128 v223, v[0:3]
	s_waitcnt vmcnt(14)
	ds_write_b128 v222, v[4:7]
	s_waitcnt vmcnt(13)
	ds_write_b128 v221, v[8:11]
	s_waitcnt vmcnt(12)
	ds_write_b128 v220, v[12:15]
	s_waitcnt vmcnt(11)
	ds_write_b128 v219, v[16:19]
	s_waitcnt vmcnt(10)
	ds_write_b128 v218, v[20:23]
	s_waitcnt vmcnt(9)
	ds_write_b128 v217, v[24:27]
	s_waitcnt vmcnt(8)
	ds_write_b128 v216, v[28:31]
	s_waitcnt vmcnt(7)
	ds_write_b128 v230, v[72:75]
	s_waitcnt vmcnt(6)
	ds_write_b128 v224, v[76:79]
	s_waitcnt vmcnt(5)
	ds_write_b128 v225, v[80:83]
	s_waitcnt vmcnt(4)
	ds_write_b128 v226, v[84:87]
	s_waitcnt vmcnt(3)
	ds_write_b128 v227, v[88:91]
	s_waitcnt vmcnt(2)
	ds_write_b128 v228, v[92:95]
	s_waitcnt vmcnt(1)
	ds_write_b128 v229, v[96:99]
	s_waitcnt vmcnt(0)
	ds_write_b128 v215, v[100:103]
	s_waitcnt lgkmcnt(0)
	s_barrier
	ds_read_b128 v[0:3], v213
	ds_read_b128 v[4:7], v213 offset:32
	s_waitcnt lgkmcnt(1)
	v_mfma_f32_32x32x16_bf16 v[96:111], v[0:3], v[112:115], 0
	ds_read_b128 v[0:3], v213 offset:64
	ds_read_b128 v[48:51], v213 offset:50720
	s_waitcnt lgkmcnt(2)
	v_mfma_f32_32x32x16_bf16 v[96:111], v[4:7], v[184:187], v[96:111]
	s_waitcnt lgkmcnt(1)
	v_mfma_f32_32x32x16_bf16 v[96:111], v[0:3], v[180:183], v[96:111]
	ds_read_b128 v[0:3], v213 offset:96
	s_waitcnt lgkmcnt(0)
	v_mfma_f32_32x32x16_bf16 v[96:111], v[0:3], v[176:179], v[96:111]
	ds_read_b128 v[0:3], v213 offset:128
	s_waitcnt lgkmcnt(0)
	v_mfma_f32_32x32x16_bf16 v[96:111], v[0:3], v[172:175], v[96:111]
	ds_read_b128 v[0:3], v213 offset:160
	s_waitcnt lgkmcnt(0)
	v_mfma_f32_32x32x16_bf16 v[96:111], v[0:3], v[168:171], v[96:111]
	ds_read_b128 v[0:3], v213 offset:192
	s_waitcnt lgkmcnt(0)
	v_mfma_f32_32x32x16_bf16 v[96:111], v[0:3], v[164:167], v[96:111]
	ds_read_b128 v[0:3], v213 offset:224
	s_waitcnt lgkmcnt(0)
	v_mfma_f32_32x32x16_bf16 v[96:111], v[0:3], v[160:163], v[96:111]
	ds_read_b128 v[0:3], v213 offset:256
	s_waitcnt lgkmcnt(0)
	v_mfma_f32_32x32x16_bf16 v[96:111], v[0:3], v[156:159], v[96:111]
	ds_read_b128 v[0:3], v213 offset:288
	s_waitcnt lgkmcnt(0)
	v_mfma_f32_32x32x16_bf16 v[96:111], v[0:3], v[152:155], v[96:111]
	ds_read_b128 v[0:3], v213 offset:320
	s_waitcnt lgkmcnt(0)
	v_mfma_f32_32x32x16_bf16 v[96:111], v[0:3], v[148:151], v[96:111]
	ds_read_b128 v[0:3], v213 offset:352
	s_waitcnt lgkmcnt(0)
	v_mfma_f32_32x32x16_bf16 v[96:111], v[0:3], v[144:147], v[96:111]
	ds_read_b128 v[0:3], v213 offset:384
	s_waitcnt lgkmcnt(0)
; #define LAS __attribute__((address_space(3)))
; __device__ __forceinline__ void xattn_core(unsigned char* ws, LAS unsigned char* lds, int b, int hd, int qb, int tid, const bf16x8 (&qf)[16]) {
;     ...
;     for (int mt = 0; mt < 8; ++mt) {
; #pragma unroll
;         for (int r = 0; r < 16; ++r) sacc[mt][r] = 0.f;
;         const LAS bf16* kp = (mt < 4 ? L0 : L1) + ((mt & 3) * 32 + r32) * XP + 8 * hh;
; #pragma unroll
;         for (int ds = 0; ds < 16; ++ds) { const bf16x8 kf = *(const LAS bf16x8*)(kp + 16 * ds); sacc[mt] = __builtin_amdgcn_mfma_f32_32x32x16_bf16(kf, qf[ds], sacc[mt], 0, 0, 0); } }
	v_mfma_f32_32x32x16_bf16 v[96:111], v[0:3], v[140:143], v[96:111]
	ds_read_b128 v[0:3], v213 offset:416
	s_waitcnt lgkmcnt(0)
	v_mfma_f32_32x32x16_bf16 v[96:111], v[0:3], v[136:139], v[96:111]
	ds_read_b128 v[0:3], v213 offset:448
	s_waitcnt lgkmcnt(0)
	v_mfma_f32_32x32x16_bf16 v[96:111], v[0:3], v[132:135], v[96:111]
	ds_read_b128 v[0:3], v213 offset:480
	s_waitcnt lgkmcnt(0)
	v_mfma_f32_32x32x16_bf16 v[96:111], v[0:3], v[128:131], v[96:111]
	ds_read_b128 v[0:3], v213 offset:16896
	s_waitcnt lgkmcnt(0)
	v_mfma_f32_32x32x16_bf16 v[32:47], v[0:3], v[112:115], 0
	ds_read_b128 v[0:3], v213 offset:16928
	s_waitcnt lgkmcnt(0)
	v_mfma_f32_32x32x16_bf16 v[32:47], v[0:3], v[184:187], v[32:47]
	ds_read_b128 v[0:3], v213 offset:16960
	s_waitcnt lgkmcnt(0)
	v_mfma_f32_32x32x16_bf16 v[32:47], v[0:3], v[180:183], v[32:47]
	ds_read_b128 v[0:3], v213 offset:16992
	s_waitcnt lgkmcnt(0)
	v_mfma_f32_32x32x16_bf16 v[32:47], v[0:3], v[176:179], v[32:47]
	ds_read_b128 v[0:3], v213 offset:17024
	s_waitcnt lgkmcnt(0)
	v_mfma_f32_32x32x16_bf16 v[32:47], v[0:3], v[172:175], v[32:47]
	ds_read_b128 v[0:3], v213 offset:17056
	s_waitcnt lgkmcnt(0)
	v_mfma_f32_32x32x16_bf16 v[32:47], v[0:3], v[168:171], v[32:47]
	ds_read_b128 v[0:3], v213 offset:17088
	s_waitcnt lgkmcnt(0)
	v_mfma_f32_32x32x16_bf16 v[32:47], v[0:3], v[164:167], v[32:47]
	ds_read_b128 v[0:3], v213 offset:17120
	s_waitcnt lgkmcnt(0)
	v_mfma_f32_32x32x16_bf16 v[32:47], v[0:3], v[160:163], v[32:47]
	ds_read_b128 v[0:3], v213 offset:17152
	s_waitcnt lgkmcnt(0)
	v_mfma_f32_32x32x16_bf16 v[32:47], v[0:3], v[156:159], v[32:47]
	ds_read_b128 v[0:3], v213 offset:17184
	s_waitcnt lgkmcnt(0)
	v_mfma_f32_32x32x16_bf16 v[32:47], v[0:3], v[152:155], v[32:47]
	ds_read_b128 v[0:3], v213 offset:17216
	s_waitcnt lgkmcnt(0)
	v_mfma_f32_32x32x16_bf16 v[32:47], v[0:3], v[148:151], v[32:47]
	ds_read_b128 v[0:3], v213 offset:17248
	s_waitcnt lgkmcnt(0)
	v_mfma_f32_32x32x16_bf16 v[32:47], v[0:3], v[144:147], v[32:47]
	ds_read_b128 v[0:3], v213 offset:17280
	s_waitcnt lgkmcnt(0)
	v_mfma_f32_32x32x16_bf16 v[32:47], v[0:3], v[140:143], v[32:47]
	ds_read_b128 v[0:3], v213 offset:17312
	s_waitcnt lgkmcnt(0)
	v_mfma_f32_32x32x16_bf16 v[32:47], v[0:3], v[136:139], v[32:47]
	ds_read_b128 v[0:3], v213 offset:17344
	s_waitcnt lgkmcnt(0)
	v_mfma_f32_32x32x16_bf16 v[32:47], v[0:3], v[132:135], v[32:47]
	ds_read_b128 v[0:3], v213 offset:17376
	s_waitcnt lgkmcnt(0)
	v_mfma_f32_32x32x16_bf16 v[32:47], v[0:3], v[128:131], v[32:47]
	ds_read_b128 v[0:3], v213 offset:33792
	s_waitcnt lgkmcnt(0)
	v_mfma_f32_32x32x16_bf16 v[16:31], v[0:3], v[112:115], 0
	ds_read_b128 v[0:3], v213 offset:33824
	s_waitcnt lgkmcnt(0)
	v_mfma_f32_32x32x16_bf16 v[16:31], v[0:3], v[184:187], v[16:31]
	ds_read_b128 v[0:3], v213 offset:33856
	s_waitcnt lgkmcnt(0)
	v_mfma_f32_32x32x16_bf16 v[16:31], v[0:3], v[180:183], v[16:31]
	ds_read_b128 v[0:3], v213 offset:33888
	s_waitcnt lgkmcnt(0)
	v_mfma_f32_32x32x16_bf16 v[16:31], v[0:3], v[176:179], v[16:31]
	ds_read_b128 v[0:3], v213 offset:33920
	s_waitcnt lgkmcnt(0)
	v_mfma_f32_32x32x16_bf16 v[16:31], v[0:3], v[172:175], v[16:31]
	ds_read_b128 v[0:3], v213 offset:33952
	s_waitcnt lgkmcnt(0)
	v_mfma_f32_32x32x16_bf16 v[16:31], v[0:3], v[168:171], v[16:31]
	ds_read_b128 v[0:3], v213 offset:33984
	s_waitcnt lgkmcnt(0)
	v_mfma_f32_32x32x16_bf16 v[16:31], v[0:3], v[164:167], v[16:31]
	ds_read_b128 v[0:3], v213 offset:34016
	s_waitcnt lgkmcnt(0)
	v_mfma_f32_32x32x16_bf16 v[16:31], v[0:3], v[160:163], v[16:31]
	ds_read_b128 v[0:3], v213 offset:34048
	s_waitcnt lgkmcnt(0)
	v_mfma_f32_32x32x16_bf16 v[16:31], v[0:3], v[156:159], v[16:31]
	ds_read_b128 v[0:3], v213 offset:34080
	s_waitcnt lgkmcnt(0)
	v_mfma_f32_32x32x16_bf16 v[16:31], v[0:3], v[152:155], v[16:31]
	ds_read_b128 v[0:3], v213 offset:34112
	s_waitcnt lgkmcnt(0)
	v_mfma_f32_32x32x16_bf16 v[16:31], v[0:3], v[148:151], v[16:31]
	ds_read_b128 v[0:3], v213 offset:34144
	s_waitcnt lgkmcnt(0)
	v_mfma_f32_32x32x16_bf16 v[16:31], v[0:3], v[144:147], v[16:31]
	ds_read_b128 v[0:3], v213 offset:34176
	s_waitcnt lgkmcnt(0)
	v_mfma_f32_32x32x16_bf16 v[16:31], v[0:3], v[140:143], v[16:31]
	ds_read_b128 v[0:3], v213 offset:34208
	s_waitcnt lgkmcnt(0)
	v_mfma_f32_32x32x16_bf16 v[16:31], v[0:3], v[136:139], v[16:31]
	ds_read_b128 v[0:3], v213 offset:34240
	s_waitcnt lgkmcnt(0)
	v_mfma_f32_32x32x16_bf16 v[16:31], v[0:3], v[132:135], v[16:31]
	ds_read_b128 v[0:3], v213 offset:34272
	s_waitcnt lgkmcnt(0)
	v_mfma_f32_32x32x16_bf16 v[16:31], v[0:3], v[128:131], v[16:31]
	ds_read_b128 v[0:3], v213 offset:50688
	s_waitcnt lgkmcnt(0)
	v_mfma_f32_32x32x16_bf16 v[0:15], v[0:3], v[112:115], 0
	v_mfma_f32_32x32x16_bf16 v[0:15], v[48:51], v[184:187], v[0:15]
	ds_read_b128 v[48:51], v213 offset:50752
	s_waitcnt lgkmcnt(0)
	v_mfma_f32_32x32x16_bf16 v[0:15], v[48:51], v[180:183], v[0:15]
	ds_read_b128 v[48:51], v213 offset:50784
	s_waitcnt lgkmcnt(0)
	v_mfma_f32_32x32x16_bf16 v[0:15], v[48:51], v[176:179], v[0:15]
	ds_read_b128 v[48:51], v213 offset:50816
	s_waitcnt lgkmcnt(0)
	v_mfma_f32_32x32x16_bf16 v[0:15], v[48:51], v[172:175], v[0:15]
	ds_read_b128 v[48:51], v213 offset:50848
	s_waitcnt lgkmcnt(0)
	v_mfma_f32_32x32x16_bf16 v[0:15], v[48:51], v[168:171], v[0:15]
	ds_read_b128 v[48:51], v213 offset:50880
	s_waitcnt lgkmcnt(0)
	v_mfma_f32_32x32x16_bf16 v[0:15], v[48:51], v[164:167], v[0:15]
	ds_read_b128 v[48:51], v213 offset:50912
	s_waitcnt lgkmcnt(0)
	v_mfma_f32_32x32x16_bf16 v[0:15], v[48:51], v[160:163], v[0:15]
	ds_read_b128 v[48:51], v213 offset:50944
	s_waitcnt lgkmcnt(0)
	v_mfma_f32_32x32x16_bf16 v[0:15], v[48:51], v[156:159], v[0:15]
	ds_read_b128 v[48:51], v213 offset:50976
	s_waitcnt lgkmcnt(0)
; #define LAS __attribute__((address_space(3)))
; __device__ __forceinline__ void xattn_core(unsigned char* ws, LAS unsigned char* lds, int b, int hd, int qb, int tid, const bf16x8 (&qf)[16]) {
;     ...
;     for (int mt = 0; mt < 8; ++mt) {
; #pragma unroll
;         for (int r = 0; r < 16; ++r) sacc[mt][r] = 0.f;
;         const LAS bf16* kp = (mt < 4 ? L0 : L1) + ((mt & 3) * 32 + r32) * XP + 8 * hh;
; #pragma unroll
;         for (int ds = 0; ds < 16; ++ds) { const bf16x8 kf = *(const LAS bf16x8*)(kp + 16 * ds); sacc[mt] = __builtin_amdgcn_mfma_f32_32x32x16_bf16(kf, qf[ds], sacc[mt], 0, 0, 0); } }
	v_mfma_f32_32x32x16_bf16 v[0:15], v[48:51], v[152:155], v[0:15]
	ds_read_b128 v[48:51], v213 offset:51008
	s_waitcnt lgkmcnt(0)
	v_mfma_f32_32x32x16_bf16 v[0:15], v[48:51], v[148:151], v[0:15]
	ds_read_b128 v[48:51], v213 offset:51040
	s_waitcnt lgkmcnt(0)
	v_mfma_f32_32x32x16_bf16 v[0:15], v[48:51], v[144:147], v[0:15]
	ds_read_b128 v[48:51], v213 offset:51072
	s_waitcnt lgkmcnt(0)
	v_mfma_f32_32x32x16_bf16 v[0:15], v[48:51], v[140:143], v[0:15]
	ds_read_b128 v[48:51], v213 offset:51104
	s_waitcnt lgkmcnt(0)
	v_mfma_f32_32x32x16_bf16 v[0:15], v[48:51], v[136:139], v[0:15]
	ds_read_b128 v[48:51], v213 offset:51136
	s_waitcnt lgkmcnt(0)
	v_mfma_f32_32x32x16_bf16 v[0:15], v[48:51], v[132:135], v[0:15]
	ds_read_b128 v[48:51], v213 offset:51168
	s_waitcnt lgkmcnt(0)
	v_mfma_f32_32x32x16_bf16 v[0:15], v[48:51], v[128:131], v[0:15]
	ds_read_b128 v[48:51], v68
	ds_read_b128 v[64:67], v68 offset:32
	s_waitcnt lgkmcnt(1)
	v_mfma_f32_32x32x16_bf16 v[48:63], v[48:51], v[112:115], 0
	s_waitcnt lgkmcnt(0)
	v_mfma_f32_32x32x16_bf16 v[48:63], v[64:67], v[184:187], v[48:63]
	ds_read_b128 v[64:67], v68 offset:64
	s_waitcnt lgkmcnt(0)
	v_mfma_f32_32x32x16_bf16 v[48:63], v[64:67], v[180:183], v[48:63]
	ds_read_b128 v[64:67], v68 offset:96
	s_waitcnt lgkmcnt(0)
	v_mfma_f32_32x32x16_bf16 v[48:63], v[64:67], v[176:179], v[48:63]
	ds_read_b128 v[64:67], v68 offset:128
	s_waitcnt lgkmcnt(0)
	v_mfma_f32_32x32x16_bf16 v[48:63], v[64:67], v[172:175], v[48:63]
	ds_read_b128 v[64:67], v68 offset:160
	s_waitcnt lgkmcnt(0)
	v_mfma_f32_32x32x16_bf16 v[48:63], v[64:67], v[168:171], v[48:63]
	ds_read_b128 v[64:67], v68 offset:192
	s_waitcnt lgkmcnt(0)
	v_mfma_f32_32x32x16_bf16 v[48:63], v[64:67], v[164:167], v[48:63]
	ds_read_b128 v[64:67], v68 offset:224
	s_waitcnt lgkmcnt(0)
	v_mfma_f32_32x32x16_bf16 v[48:63], v[64:67], v[160:163], v[48:63]
	ds_read_b128 v[64:67], v68 offset:256
	s_waitcnt lgkmcnt(0)
	v_mfma_f32_32x32x16_bf16 v[48:63], v[64:67], v[156:159], v[48:63]
	ds_read_b128 v[64:67], v68 offset:288
	s_waitcnt lgkmcnt(0)
	v_mfma_f32_32x32x16_bf16 v[48:63], v[64:67], v[152:155], v[48:63]
	ds_read_b128 v[64:67], v68 offset:320
	s_waitcnt lgkmcnt(0)
	v_mfma_f32_32x32x16_bf16 v[48:63], v[64:67], v[148:151], v[48:63]
	ds_read_b128 v[64:67], v68 offset:352
	s_waitcnt lgkmcnt(0)
	v_mfma_f32_32x32x16_bf16 v[48:63], v[64:67], v[144:147], v[48:63]
	ds_read_b128 v[64:67], v68 offset:384
	s_waitcnt lgkmcnt(0)
	v_mfma_f32_32x32x16_bf16 v[48:63], v[64:67], v[140:143], v[48:63]
	ds_read_b128 v[64:67], v68 offset:416
	s_waitcnt lgkmcnt(0)
	v_mfma_f32_32x32x16_bf16 v[48:63], v[64:67], v[136:139], v[48:63]
	ds_read_b128 v[64:67], v68 offset:448
	s_waitcnt lgkmcnt(0)
	v_mfma_f32_32x32x16_bf16 v[48:63], v[64:67], v[132:135], v[48:63]
	ds_read_b128 v[64:67], v68 offset:480
	s_waitcnt lgkmcnt(0)
	v_mfma_f32_32x32x16_bf16 v[48:63], v[64:67], v[128:131], v[48:63]
	ds_read_b128 v[64:67], v189 offset:16896
	ds_read_b128 v[68:71], v189 offset:16928
	ds_read_b128 v[116:119], v189 offset:33824
	ds_read_b128 v[232:235], v189 offset:50720
	s_waitcnt lgkmcnt(3)
	v_mfma_f32_32x32x16_bf16 v[80:95], v[64:67], v[112:115], 0
	ds_read_b128 v[64:67], v189 offset:16960
	s_waitcnt lgkmcnt(3)
	v_mfma_f32_32x32x16_bf16 v[80:95], v[68:71], v[184:187], v[80:95]
	s_waitcnt lgkmcnt(0)
	v_mfma_f32_32x32x16_bf16 v[80:95], v[64:67], v[180:183], v[80:95]
	ds_read_b128 v[64:67], v189 offset:16992
	s_waitcnt lgkmcnt(0)
	v_mfma_f32_32x32x16_bf16 v[80:95], v[64:67], v[176:179], v[80:95]
	ds_read_b128 v[64:67], v189 offset:17024
	s_waitcnt lgkmcnt(0)
	v_mfma_f32_32x32x16_bf16 v[80:95], v[64:67], v[172:175], v[80:95]
	ds_read_b128 v[64:67], v189 offset:17056
	s_waitcnt lgkmcnt(0)
	v_mfma_f32_32x32x16_bf16 v[80:95], v[64:67], v[168:171], v[80:95]
	ds_read_b128 v[64:67], v189 offset:17088
	s_waitcnt lgkmcnt(0)
	v_mfma_f32_32x32x16_bf16 v[80:95], v[64:67], v[164:167], v[80:95]
	ds_read_b128 v[64:67], v189 offset:17120
	s_waitcnt lgkmcnt(0)
	v_mfma_f32_32x32x16_bf16 v[80:95], v[64:67], v[160:163], v[80:95]
	ds_read_b128 v[64:67], v189 offset:17152
	s_waitcnt lgkmcnt(0)
	v_mfma_f32_32x32x16_bf16 v[80:95], v[64:67], v[156:159], v[80:95]
	ds_read_b128 v[64:67], v189 offset:17184
	s_waitcnt lgkmcnt(0)
	v_mfma_f32_32x32x16_bf16 v[80:95], v[64:67], v[152:155], v[80:95]
	ds_read_b128 v[64:67], v189 offset:17216
	s_waitcnt lgkmcnt(0)
	v_mfma_f32_32x32x16_bf16 v[80:95], v[64:67], v[148:151], v[80:95]
	ds_read_b128 v[64:67], v189 offset:17248
	s_waitcnt lgkmcnt(0)
	v_mfma_f32_32x32x16_bf16 v[80:95], v[64:67], v[144:147], v[80:95]
	ds_read_b128 v[64:67], v189 offset:17280
	s_waitcnt lgkmcnt(0)
	v_mfma_f32_32x32x16_bf16 v[80:95], v[64:67], v[140:143], v[80:95]
	ds_read_b128 v[64:67], v189 offset:17312
	s_waitcnt lgkmcnt(0)
	v_mfma_f32_32x32x16_bf16 v[80:95], v[64:67], v[136:139], v[80:95]
	ds_read_b128 v[64:67], v189 offset:17344
	s_waitcnt lgkmcnt(0)
	v_mfma_f32_32x32x16_bf16 v[80:95], v[64:67], v[132:135], v[80:95]
	ds_read_b128 v[64:67], v189 offset:17376
	s_waitcnt lgkmcnt(0)
	v_mfma_f32_32x32x16_bf16 v[80:95], v[64:67], v[128:131], v[80:95]
	ds_read_b128 v[64:67], v189 offset:33792
	s_waitcnt lgkmcnt(0)
	v_mfma_f32_32x32x16_bf16 v[64:79], v[64:67], v[112:115], 0
	v_mfma_f32_32x32x16_bf16 v[64:79], v[116:119], v[184:187], v[64:79]
	ds_read_b128 v[116:119], v189 offset:33856
	s_waitcnt lgkmcnt(0)
	v_mfma_f32_32x32x16_bf16 v[64:79], v[116:119], v[180:183], v[64:79]
	ds_read_b128 v[116:119], v189 offset:33888
	s_waitcnt lgkmcnt(0)
	v_mfma_f32_32x32x16_bf16 v[64:79], v[116:119], v[176:179], v[64:79]
	ds_read_b128 v[116:119], v189 offset:33920
	s_waitcnt lgkmcnt(0)
	v_mfma_f32_32x32x16_bf16 v[64:79], v[116:119], v[172:175], v[64:79]
	ds_read_b128 v[116:119], v189 offset:33952
	s_waitcnt lgkmcnt(0)
; #define LAS __attribute__((address_space(3)))
; __device__ __forceinline__ void stage_half(const bf16* g, LAS bf16* dst, int tid) {
;     v4u t[8];
; #pragma unroll
;     for (int i = 0; i < 8; ++i) { const int ch = tid + i * NT, r = ch >> 5, cc = ch & 31; t[i] = *(const v4u*)(g + (size_t)r * 1024 + cc * 8); }
; #pragma unroll
;     for (int i = 0; i < 8; ++i) { const int ch = tid + i * NT, r = ch >> 5, cc = ch & 31; *(LAS v4u*)(dst + r * XP + cc * 8) = t[i]; }
; }
; __device__ __forceinline__ void xattn_core(unsigned char* ws, LAS unsigned char* lds, int b, int hd, int qb, int tid, const bf16x8 (&qf)[16]) {
;     ...
;     for (int mt = 0; mt < 8; ++mt) {
; #pragma unroll
;         for (int r = 0; r < 16; ++r) sacc[mt][r] = 0.f;
;         const LAS bf16* kp = (mt < 4 ? L0 : L1) + ((mt & 3) * 32 + r32) * XP + 8 * hh;
; #pragma unroll
;         for (int ds = 0; ds < 16; ++ds) { const bf16x8 kf = *(const LAS bf16x8*)(kp + 16 * ds); sacc[mt] = __builtin_amdgcn_mfma_f32_32x32x16_bf16(kf, qf[ds], sacc[mt], 0, 0, 0); } }
;     __syncthreads();
;     stage_half(Vg, L0, tid); stage_half(Vg + (size_t)128 * 1024, L1, tid);
	v_mfma_f32_32x32x16_bf16 v[64:79], v[116:119], v[168:171], v[64:79]
	ds_read_b128 v[116:119], v189 offset:33984
	s_waitcnt lgkmcnt(0)
	v_mfma_f32_32x32x16_bf16 v[64:79], v[116:119], v[164:167], v[64:79]
	ds_read_b128 v[116:119], v189 offset:34016
	s_waitcnt lgkmcnt(0)
	v_mfma_f32_32x32x16_bf16 v[64:79], v[116:119], v[160:163], v[64:79]
	ds_read_b128 v[116:119], v189 offset:34048
	s_waitcnt lgkmcnt(0)
	v_mfma_f32_32x32x16_bf16 v[64:79], v[116:119], v[156:159], v[64:79]
	ds_read_b128 v[116:119], v189 offset:34080
	s_waitcnt lgkmcnt(0)
	v_mfma_f32_32x32x16_bf16 v[64:79], v[116:119], v[152:155], v[64:79]
	ds_read_b128 v[116:119], v189 offset:34112
	s_waitcnt lgkmcnt(0)
	v_mfma_f32_32x32x16_bf16 v[64:79], v[116:119], v[148:151], v[64:79]
	ds_read_b128 v[116:119], v189 offset:34144
	s_waitcnt lgkmcnt(0)
	v_mfma_f32_32x32x16_bf16 v[64:79], v[116:119], v[144:147], v[64:79]
	ds_read_b128 v[116:119], v189 offset:34176
	s_waitcnt lgkmcnt(0)
	v_mfma_f32_32x32x16_bf16 v[64:79], v[116:119], v[140:143], v[64:79]
	ds_read_b128 v[116:119], v189 offset:34208
	s_waitcnt lgkmcnt(0)
	v_mfma_f32_32x32x16_bf16 v[64:79], v[116:119], v[136:139], v[64:79]
	ds_read_b128 v[116:119], v189 offset:34240
	s_waitcnt lgkmcnt(0)
	v_mfma_f32_32x32x16_bf16 v[64:79], v[116:119], v[132:135], v[64:79]
	ds_read_b128 v[116:119], v189 offset:34272
	s_waitcnt lgkmcnt(0)
	v_mfma_f32_32x32x16_bf16 v[64:79], v[116:119], v[128:131], v[64:79]
	ds_read_b128 v[116:119], v189 offset:50688
	s_waitcnt lgkmcnt(0)
	v_mfma_f32_32x32x16_bf16 v[112:127], v[116:119], v[112:115], 0
	v_mfma_f32_32x32x16_bf16 v[112:127], v[232:235], v[184:187], v[112:127]
	ds_read_b128 v[184:187], v189 offset:50752
	s_waitcnt lgkmcnt(0)
	v_mfma_f32_32x32x16_bf16 v[112:127], v[184:187], v[180:183], v[112:127]
	ds_read_b128 v[180:183], v189 offset:50784
	s_waitcnt lgkmcnt(0)
	v_mfma_f32_32x32x16_bf16 v[112:127], v[180:183], v[176:179], v[112:127]
	ds_read_b128 v[176:179], v189 offset:50816
	s_waitcnt lgkmcnt(0)
	v_mfma_f32_32x32x16_bf16 v[112:127], v[176:179], v[172:175], v[112:127]
	ds_read_b128 v[172:175], v189 offset:50848
	s_waitcnt lgkmcnt(0)
	v_mfma_f32_32x32x16_bf16 v[112:127], v[172:175], v[168:171], v[112:127]
	ds_read_b128 v[168:171], v189 offset:50880
	s_waitcnt lgkmcnt(0)
	v_mfma_f32_32x32x16_bf16 v[112:127], v[168:171], v[164:167], v[112:127]
	ds_read_b128 v[164:167], v189 offset:50912
	s_waitcnt lgkmcnt(0)
	v_mfma_f32_32x32x16_bf16 v[112:127], v[164:167], v[160:163], v[112:127]
	ds_read_b128 v[160:163], v189 offset:50944
	s_waitcnt lgkmcnt(0)
	v_mfma_f32_32x32x16_bf16 v[112:127], v[160:163], v[156:159], v[112:127]
	ds_read_b128 v[156:159], v189 offset:50976
	v_lshl_add_u64 v[160:161], s[16:17], 0, v[190:191]
	s_waitcnt lgkmcnt(0)
	v_mfma_f32_32x32x16_bf16 v[112:127], v[156:159], v[152:155], v[112:127]
	ds_read_b128 v[152:155], v189 offset:51008
	v_lshl_add_u64 v[156:157], v[160:161], 0, s[14:15]
	s_mov_b64 s[14:15], 0x5840000
	s_waitcnt lgkmcnt(0)
	v_mfma_f32_32x32x16_bf16 v[112:127], v[152:155], v[148:151], v[112:127]
	ds_read_b128 v[148:151], v189 offset:51040
	v_lshl_add_u64 v[152:153], v[156:157], 0, v[204:205]
	s_waitcnt lgkmcnt(0)
	v_mfma_f32_32x32x16_bf16 v[112:127], v[148:151], v[144:147], v[112:127]
	ds_read_b128 v[144:147], v189 offset:51072
	v_lshl_add_u64 v[148:149], v[156:157], 0, v[202:203]
	s_waitcnt lgkmcnt(0)
	v_mfma_f32_32x32x16_bf16 v[112:127], v[144:147], v[140:143], v[112:127]
	ds_read_b128 v[140:143], v189 offset:51104
	v_lshl_add_u64 v[144:145], v[156:157], 0, v[200:201]
	s_waitcnt lgkmcnt(0)
	v_mfma_f32_32x32x16_bf16 v[112:127], v[140:143], v[136:139], v[112:127]
	ds_read_b128 v[136:139], v189 offset:51136
	v_lshl_add_u64 v[140:141], v[156:157], 0, v[198:199]
	s_waitcnt lgkmcnt(0)
	v_mfma_f32_32x32x16_bf16 v[112:127], v[136:139], v[132:135], v[112:127]
	ds_read_b128 v[132:135], v189 offset:51168
	s_waitcnt lgkmcnt(0)
	s_barrier
	v_lshl_add_u64 v[136:137], v[156:157], 0, v[196:197]
	global_load_dwordx4 v[136:139], v[136:137], off
	v_mov_b32_e32 v189, v191
	v_mfma_f32_32x32x16_bf16 v[112:127], v[132:135], v[128:131], v[112:127]
	v_lshl_add_u64 v[128:129], v[156:157], 0, v[192:193]
	global_load_dwordx4 v[128:131], v[128:129], off
	v_lshl_add_u64 v[132:133], v[156:157], 0, v[194:195]
	global_load_dwordx4 v[132:135], v[132:133], off
	v_lshl_add_u64 v[156:157], v[156:157], 0, v[206:207]
	global_load_dwordx4 v[140:143], v[140:141], off
	s_nop 0
	global_load_dwordx4 v[144:147], v[144:145], off
	s_nop 0
	global_load_dwordx4 v[148:151], v[148:149], off
	s_nop 0
	global_load_dwordx4 v[152:155], v[152:153], off
	s_nop 0
	global_load_dwordx4 v[156:159], v[156:157], off
	s_waitcnt vmcnt(6)
	ds_write_b128 v223, v[128:131]
	s_waitcnt vmcnt(5)
	ds_write_b128 v222, v[132:135]
	ds_write_b128 v221, v[136:139]
	s_waitcnt vmcnt(4)
	ds_write_b128 v220, v[140:143]
	s_waitcnt vmcnt(3)
	ds_write_b128 v219, v[144:147]
	s_waitcnt vmcnt(2)
	ds_write_b128 v218, v[148:151]
	s_waitcnt vmcnt(1)
	ds_write_b128 v217, v[152:155]
	s_waitcnt vmcnt(0)
	ds_write_b128 v216, v[156:159]
	v_lshl_add_u64 v[156:157], v[160:161], 0, s[14:15]
	v_lshl_add_u64 v[128:129], v[156:157], 0, v[192:193]
	global_load_dwordx4 v[128:131], v[128:129], off
	v_lshl_add_u64 v[132:133], v[156:157], 0, v[194:195]
	global_load_dwordx4 v[132:135], v[132:133], off
	v_lshl_add_u64 v[136:137], v[156:157], 0, v[196:197]
	global_load_dwordx4 v[136:139], v[136:137], off
	v_lshl_add_u64 v[140:141], v[156:157], 0, v[198:199]
	global_load_dwordx4 v[140:143], v[140:141], off
	v_lshl_add_u64 v[144:145], v[156:157], 0, v[200:201]
	global_load_dwordx4 v[144:147], v[144:145], off
	v_lshl_add_u64 v[148:149], v[156:157], 0, v[202:203]
	global_load_dwordx4 v[148:151], v[148:149], off
	v_lshl_add_u64 v[152:153], v[156:157], 0, v[204:205]
	global_load_dwordx4 v[152:155], v[152:153], off
	v_lshl_add_u64 v[156:157], v[156:157], 0, v[206:207]
	global_load_dwordx4 v[156:159], v[156:157], off
	s_waitcnt vmcnt(7)
; __device__ __forceinline__ unsigned pk2(float lo, float hi) { return pg8::cvt_pk_bf16(lo, hi); }
; __device__ __forceinline__ void xattn_core(unsigned char* ws, LAS unsigned char* lds, int b, int hd, int qb, int tid, const bf16x8 (&qf)[16]) {
;     ...
;     stage_half(Vg, L0, tid); stage_half(Vg + (size_t)128 * 1024, L1, tid);
;     float mx = -3.0e38f;
; #pragma unroll
;     for (int mt = 0; mt < 8; ++mt)
; #pragma unroll
;         for (int r = 0; r < 16; ++r) mx = fmaxf(mx, sacc[mt][r]);
;     mx = fmaxf(mx, __shfl_xor(mx, 32));
;     float sum = 0.f; bf16x8 pf[8][2];
; #pragma unroll
;     for (int mt = 0; mt < 8; ++mt) {
;         float e[16];
; #pragma unroll
;         for (int r = 0; r < 16; ++r) { e[r] = __expf(sacc[mt][r] - mx); sum += e[r]; }
; #pragma unroll
;         for (int s = 0; s < 2; ++s) { v4u w; w.x = pk2(e[8 * s], e[8 * s + 1]); w.y = pk2(e[8 * s + 2], e[8 * s + 3]); w.z = pk2(e[8 * s + 4], e[8 * s + 5]); w.w = pk2(e[8 * s + 6], e[8 * s + 7]); pf[mt][s] = __builtin_bit_cast(bf16x8, w); }
	ds_write_b128 v230, v[128:131]
	s_waitcnt vmcnt(6)
	ds_write_b128 v224, v[132:135]
	s_waitcnt vmcnt(5)
	ds_write_b128 v225, v[136:139]
	s_waitcnt vmcnt(4)
	ds_write_b128 v226, v[140:143]
	s_waitcnt vmcnt(3)
	ds_write_b128 v227, v[144:147]
	s_waitcnt vmcnt(2)
	ds_write_b128 v228, v[148:151]
	s_waitcnt vmcnt(1)
	ds_write_b128 v229, v[152:155]
	s_waitcnt vmcnt(0)
	ds_write_b128 v215, v[156:159]
	v_max3_f32 v128, v96, s7, v97
	v_max3_f32 v128, v128, v98, v99
	v_max3_f32 v128, v128, v100, v101
	v_max3_f32 v128, v128, v102, v103
	v_max3_f32 v128, v128, v104, v105
	v_max3_f32 v128, v128, v106, v107
	v_max3_f32 v128, v128, v108, v109
	v_max3_f32 v128, v128, v110, v111
	v_max3_f32 v128, v128, v32, v33
	v_max3_f32 v128, v128, v34, v35
	v_max3_f32 v128, v128, v36, v37
	v_max3_f32 v128, v128, v38, v39
	v_max3_f32 v128, v128, v40, v41
	v_max3_f32 v128, v128, v42, v43
	v_max3_f32 v128, v128, v44, v45
	v_max3_f32 v128, v128, v46, v47
	v_max3_f32 v128, v128, v16, v17
	v_max3_f32 v128, v128, v18, v19
	v_max3_f32 v128, v128, v20, v21
	v_max3_f32 v128, v128, v22, v23
	v_max3_f32 v128, v128, v24, v25
	v_max3_f32 v128, v128, v26, v27
	v_max3_f32 v128, v128, v28, v29
	v_max3_f32 v128, v128, v30, v31
	v_max3_f32 v128, v128, v0, v1
	v_max3_f32 v128, v128, v2, v3
	v_max3_f32 v128, v128, v4, v5
	v_max3_f32 v128, v128, v6, v7
	v_max3_f32 v128, v128, v8, v9
	v_max3_f32 v128, v128, v10, v11
	v_max3_f32 v128, v128, v12, v13
	v_max3_f32 v128, v128, v14, v15
	v_max3_f32 v128, v128, v48, v49
	v_max3_f32 v128, v128, v50, v51
	v_max3_f32 v128, v128, v52, v53
	v_max3_f32 v128, v128, v54, v55
	v_max3_f32 v128, v128, v56, v57
	v_max3_f32 v128, v128, v58, v59
	v_max3_f32 v128, v128, v60, v61
	v_max3_f32 v128, v128, v62, v63
	v_max3_f32 v128, v128, v80, v81
	v_max3_f32 v128, v128, v82, v83
	v_max3_f32 v128, v128, v84, v85
	v_max3_f32 v128, v128, v86, v87
	v_max3_f32 v128, v128, v88, v89
	v_max3_f32 v128, v128, v90, v91
	v_max3_f32 v128, v128, v92, v93
	v_max3_f32 v128, v128, v94, v95
	v_max3_f32 v128, v128, v64, v65
	v_max3_f32 v128, v128, v66, v67
	v_max3_f32 v128, v128, v68, v69
	v_max3_f32 v128, v128, v70, v71
	v_max3_f32 v128, v128, v72, v73
	v_max3_f32 v128, v128, v74, v75
	v_max3_f32 v128, v128, v76, v77
	v_max3_f32 v128, v128, v78, v79
	v_max3_f32 v128, v128, v112, v113
	v_max3_f32 v128, v128, v114, v115
	v_max3_f32 v128, v128, v116, v117
	v_max3_f32 v128, v128, v118, v119
	v_max3_f32 v128, v128, v120, v121
	v_max3_f32 v128, v128, v122, v123
	v_max3_f32 v128, v128, v124, v125
	v_max3_f32 v129, v128, v126, v127
	v_mbcnt_lo_u32_b32 v128, -1, 0
	v_mbcnt_hi_u32_b32 v128, -1, v128
	v_and_b32_e32 v131, 64, v128
	v_xor_b32_e32 v130, 32, v128
	v_add_u32_e32 v131, 64, v131
	v_cmp_lt_i32_e32 vcc, v130, v131
	s_waitcnt lgkmcnt(0)
	s_barrier
	v_cndmask_b32_e32 v128, v128, v130, vcc
	v_lshlrev_b32_e32 v128, 2, v128
	ds_bpermute_b32 v130, v128, v129
	s_waitcnt lgkmcnt(0)
	v_max_f32_e32 v130, v130, v130
	v_max_f32_e32 v129, v129, v130
	v_sub_f32_e32 v96, v96, v129
	v_mul_f32_e32 v96, 0x3fb8aa3b, v96
	v_exp_f32_e32 v130, v96
	v_sub_f32_e32 v96, v97, v129
	v_mul_f32_e32 v96, 0x3fb8aa3b, v96
	v_exp_f32_e32 v131, v96
	v_sub_f32_e32 v96, v98, v129
	v_mul_f32_e32 v96, 0x3fb8aa3b, v96
	v_exp_f32_e32 v132, v96
	v_sub_f32_e32 v96, v99, v129
	v_mul_f32_e32 v96, 0x3fb8aa3b, v96
	v_exp_f32_e32 v133, v96
	v_sub_f32_e32 v96, v100, v129
	v_mul_f32_e32 v96, 0x3fb8aa3b, v96
	v_exp_f32_e32 v134, v96
	v_sub_f32_e32 v96, v101, v129
	v_mul_f32_e32 v96, 0x3fb8aa3b, v96
	v_exp_f32_e32 v135, v96
	v_sub_f32_e32 v96, v102, v129
	v_mul_f32_e32 v96, 0x3fb8aa3b, v96
	v_exp_f32_e32 v136, v96
	v_sub_f32_e32 v96, v103, v129
	v_mul_f32_e32 v96, 0x3fb8aa3b, v96
	v_exp_f32_e32 v137, v96
	v_sub_f32_e32 v96, v104, v129
	v_mul_f32_e32 v96, 0x3fb8aa3b, v96
	v_exp_f32_e32 v104, v96
	v_sub_f32_e32 v96, v105, v129
	v_mul_f32_e32 v96, 0x3fb8aa3b, v96
	v_exp_f32_e32 v105, v96
	v_sub_f32_e32 v96, v106, v129
	v_mul_f32_e32 v96, 0x3fb8aa3b, v96
	v_exp_f32_e32 v106, v96
	v_sub_f32_e32 v96, v107, v129
	v_mul_f32_e32 v96, 0x3fb8aa3b, v96
	v_exp_f32_e32 v107, v96
	v_sub_f32_e32 v96, v108, v129
	v_mul_f32_e32 v96, 0x3fb8aa3b, v96
	v_exp_f32_e32 v108, v96
	v_sub_f32_e32 v96, v109, v129
	v_mul_f32_e32 v96, 0x3fb8aa3b, v96
	v_exp_f32_e32 v109, v96
	v_sub_f32_e32 v96, v110, v129
	v_mul_f32_e32 v96, 0x3fb8aa3b, v96
	v_exp_f32_e32 v110, v96
	v_sub_f32_e32 v96, v111, v129
	v_mul_f32_e32 v96, 0x3fb8aa3b, v96
	v_exp_f32_e32 v111, v96
	v_cvt_pk_bf16_f32 v96, v130, v131
	v_add_f32_e32 v130, 0, v130
	v_add_f32_e32 v130, v131, v130
	v_add_f32_e32 v130, v132, v130
	v_add_f32_e32 v130, v133, v130
	v_add_f32_e32 v130, v134, v130
	v_add_f32_e32 v130, v135, v130
	v_add_f32_e32 v130, v136, v130
	v_add_f32_e32 v130, v137, v130
	v_sub_f32_e32 v32, v32, v129
	v_cvt_pk_bf16_f32 v100, v104, v105
	v_add_f32_e32 v104, v104, v130
	v_mul_f32_e32 v32, 0x3fb8aa3b, v32
	v_add_f32_e32 v104, v105, v104
	v_exp_f32_e32 v105, v32
	v_sub_f32_e32 v32, v33, v129
	v_mul_f32_e32 v32, 0x3fb8aa3b, v32
	v_cvt_pk_bf16_f32 v101, v106, v107
	v_add_f32_e32 v104, v106, v104
	v_exp_f32_e32 v106, v32
	v_sub_f32_e32 v32, v34, v129
	v_mul_f32_e32 v32, 0x3fb8aa3b, v32
	v_add_f32_e32 v104, v107, v104
	v_exp_f32_e32 v107, v32
	v_sub_f32_e32 v32, v35, v129
	v_mul_f32_e32 v32, 0x3fb8aa3b, v32
	v_cvt_pk_bf16_f32 v102, v108, v109
	v_add_f32_e32 v104, v108, v104
	v_exp_f32_e32 v108, v32
	v_sub_f32_e32 v32, v36, v129
	v_mul_f32_e32 v32, 0x3fb8aa3b, v32
	v_add_f32_e32 v104, v109, v104
	v_exp_f32_e32 v109, v32
	v_sub_f32_e32 v32, v37, v129
	v_mul_f32_e32 v32, 0x3fb8aa3b, v32
	v_cvt_pk_bf16_f32 v103, v110, v111
	v_add_f32_e32 v104, v110, v104
	v_exp_f32_e32 v110, v32
	v_sub_f32_e32 v32, v38, v129
; __device__ __forceinline__ unsigned pk2(float lo, float hi) { return pg8::cvt_pk_bf16(lo, hi); }
; __device__ __forceinline__ void xattn_core(unsigned char* ws, LAS unsigned char* lds, int b, int hd, int qb, int tid, const bf16x8 (&qf)[16]) {
;     ...
;     float sum = 0.f; bf16x8 pf[8][2];
; #pragma unroll
;     for (int mt = 0; mt < 8; ++mt) {
;         float e[16];
; #pragma unroll
;         for (int r = 0; r < 16; ++r) { e[r] = __expf(sacc[mt][r] - mx); sum += e[r]; }
; #pragma unroll
;         for (int s = 0; s < 2; ++s) { v4u w; w.x = pk2(e[8 * s], e[8 * s + 1]); w.y = pk2(e[8 * s + 2], e[8 * s + 3]); w.z = pk2(e[8 * s + 4], e[8 * s + 5]); w.w = pk2(e[8 * s + 6], e[8 * s + 7]); pf[mt][s] = __builtin_bit_cast(bf16x8, w); }
;     }
	v_mul_f32_e32 v32, 0x3fb8aa3b, v32
	v_add_f32_e32 v104, v111, v104
	v_exp_f32_e32 v111, v32
	v_sub_f32_e32 v32, v39, v129
	v_mul_f32_e32 v32, 0x3fb8aa3b, v32
	v_exp_f32_e32 v130, v32
	v_sub_f32_e32 v32, v40, v129
	v_mul_f32_e32 v32, 0x3fb8aa3b, v32
	v_add_f32_e32 v104, v105, v104
	v_exp_f32_e32 v40, v32
	v_sub_f32_e32 v32, v41, v129
	v_add_f32_e32 v104, v106, v104
	v_mul_f32_e32 v32, 0x3fb8aa3b, v32
	v_add_f32_e32 v104, v107, v104
	v_exp_f32_e32 v41, v32
	v_sub_f32_e32 v32, v42, v129
	v_add_f32_e32 v104, v108, v104
	v_mul_f32_e32 v32, 0x3fb8aa3b, v32
	v_add_f32_e32 v104, v109, v104
	v_exp_f32_e32 v42, v32
	v_sub_f32_e32 v32, v43, v129
	v_add_f32_e32 v104, v110, v104
	v_mul_f32_e32 v32, 0x3fb8aa3b, v32
	v_add_f32_e32 v104, v111, v104
	v_exp_f32_e32 v43, v32
	v_sub_f32_e32 v32, v44, v129
	v_add_f32_e32 v104, v130, v104
	v_sub_f32_e32 v16, v16, v129
	v_mul_f32_e32 v32, 0x3fb8aa3b, v32
	v_cvt_pk_bf16_f32 v36, v40, v41
	v_add_f32_e32 v40, v40, v104
	v_mul_f32_e32 v16, 0x3fb8aa3b, v16
	v_exp_f32_e32 v44, v32
	v_sub_f32_e32 v32, v45, v129
	v_add_f32_e32 v40, v41, v40
	v_exp_f32_e32 v41, v16
	v_sub_f32_e32 v16, v17, v129
	v_mul_f32_e32 v32, 0x3fb8aa3b, v32
	v_mul_f32_e32 v16, 0x3fb8aa3b, v16
	v_exp_f32_e32 v45, v32
	v_sub_f32_e32 v32, v46, v129
	v_cvt_pk_bf16_f32 v37, v42, v43
	v_add_f32_e32 v40, v42, v40
	v_exp_f32_e32 v42, v16
	v_sub_f32_e32 v16, v18, v129
	v_mul_f32_e32 v32, 0x3fb8aa3b, v32
	v_mul_f32_e32 v16, 0x3fb8aa3b, v16
	v_exp_f32_e32 v46, v32
	v_sub_f32_e32 v32, v47, v129
	v_add_f32_e32 v40, v43, v40
	v_exp_f32_e32 v43, v16
	v_sub_f32_e32 v16, v19, v129
	v_mul_f32_e32 v32, 0x3fb8aa3b, v32
	v_mul_f32_e32 v16, 0x3fb8aa3b, v16
	v_exp_f32_e32 v47, v32
	v_cvt_pk_bf16_f32 v38, v44, v45
	v_add_f32_e32 v40, v44, v40
	v_exp_f32_e32 v44, v16
	v_sub_f32_e32 v16, v20, v129
	v_mul_f32_e32 v16, 0x3fb8aa3b, v16
	v_add_f32_e32 v40, v45, v40
	v_exp_f32_e32 v45, v16
	v_sub_f32_e32 v16, v21, v129
	v_mul_f32_e32 v16, 0x3fb8aa3b, v16
	v_cvt_pk_bf16_f32 v39, v46, v47
	v_add_f32_e32 v40, v46, v40
	v_exp_f32_e32 v46, v16
	v_sub_f32_e32 v16, v22, v129
	v_mul_f32_e32 v16, 0x3fb8aa3b, v16
	v_add_f32_e32 v40, v47, v40
	v_exp_f32_e32 v47, v16
	v_sub_f32_e32 v16, v23, v129
	v_mul_f32_e32 v16, 0x3fb8aa3b, v16
	v_exp_f32_e32 v104, v16
	v_sub_f32_e32 v16, v24, v129
	v_mul_f32_e32 v16, 0x3fb8aa3b, v16
	v_exp_f32_e32 v24, v16
	v_sub_f32_e32 v16, v25, v129
	v_mul_f32_e32 v16, 0x3fb8aa3b, v16
	v_exp_f32_e32 v25, v16
	v_sub_f32_e32 v16, v26, v129
	v_mul_f32_e32 v16, 0x3fb8aa3b, v16
	v_add_f32_e32 v40, v41, v40
	v_exp_f32_e32 v26, v16
	v_sub_f32_e32 v16, v27, v129
	v_add_f32_e32 v40, v42, v40
	v_mul_f32_e32 v16, 0x3fb8aa3b, v16
	v_add_f32_e32 v40, v43, v40
	v_exp_f32_e32 v27, v16
	v_sub_f32_e32 v16, v28, v129
	v_add_f32_e32 v40, v44, v40
	v_mul_f32_e32 v16, 0x3fb8aa3b, v16
	v_add_f32_e32 v40, v45, v40
	v_exp_f32_e32 v28, v16
	v_sub_f32_e32 v16, v29, v129
	v_add_f32_e32 v40, v46, v40
	v_mul_f32_e32 v16, 0x3fb8aa3b, v16
	v_add_f32_e32 v40, v47, v40
	v_exp_f32_e32 v29, v16
	v_sub_f32_e32 v16, v30, v129
	v_add_f32_e32 v40, v104, v40
	v_mul_f32_e32 v16, 0x3fb8aa3b, v16
	v_cvt_pk_bf16_f32 v20, v24, v25
	v_add_f32_e32 v24, v24, v40
	v_exp_f32_e32 v30, v16
	v_sub_f32_e32 v16, v31, v129
	v_add_f32_e32 v24, v25, v24
	v_mul_f32_e32 v16, 0x3fb8aa3b, v16
	v_add_f32_e32 v24, v26, v24
	v_sub_f32_e32 v0, v0, v129
	v_sub_f32_e32 v1, v1, v129
	v_exp_f32_e32 v31, v16
	v_add_f32_e32 v24, v27, v24
	v_mul_f32_e32 v0, 0x3fb8aa3b, v0
	v_mul_f32_e32 v1, 0x3fb8aa3b, v1
	v_add_f32_e32 v24, v28, v24
	v_exp_f32_e32 v0, v0
	v_exp_f32_e32 v1, v1
	v_sub_f32_e32 v2, v2, v129
	v_add_f32_e32 v24, v29, v24
	v_mul_f32_e32 v2, 0x3fb8aa3b, v2
	v_sub_f32_e32 v3, v3, v129
	v_add_f32_e32 v24, v30, v24
	v_exp_f32_e32 v2, v2
	v_mul_f32_e32 v3, 0x3fb8aa3b, v3
	v_sub_f32_e32 v4, v4, v129
	v_add_f32_e32 v40, v31, v24
	v_exp_f32_e32 v3, v3
	v_mul_f32_e32 v4, 0x3fb8aa3b, v4
	v_sub_f32_e32 v5, v5, v129
	v_exp_f32_e32 v4, v4
	v_mul_f32_e32 v5, 0x3fb8aa3b, v5
	v_sub_f32_e32 v6, v6, v129
	v_cvt_pk_bf16_f32 v24, v0, v1
	v_add_f32_e32 v0, v0, v40
	v_exp_f32_e32 v5, v5
	v_mul_f32_e32 v6, 0x3fb8aa3b, v6
	v_sub_f32_e32 v7, v7, v129
	v_add_f32_e32 v0, v1, v0
	v_exp_f32_e32 v6, v6
	v_mul_f32_e32 v7, 0x3fb8aa3b, v7
	v_sub_f32_e32 v8, v8, v129
	v_add_f32_e32 v0, v2, v0
	v_exp_f32_e32 v7, v7
	v_mul_f32_e32 v8, 0x3fb8aa3b, v8
	v_sub_f32_e32 v9, v9, v129
	v_add_f32_e32 v0, v3, v0
	v_exp_f32_e32 v8, v8
	v_mul_f32_e32 v9, 0x3fb8aa3b, v9
	v_sub_f32_e32 v10, v10, v129
	v_add_f32_e32 v0, v4, v0
	v_exp_f32_e32 v9, v9
	v_mul_f32_e32 v10, 0x3fb8aa3b, v10
	v_sub_f32_e32 v11, v11, v129
	v_add_f32_e32 v0, v5, v0
	v_exp_f32_e32 v10, v10
	v_mul_f32_e32 v11, 0x3fb8aa3b, v11
	v_sub_f32_e32 v12, v12, v129
	v_add_f32_e32 v0, v6, v0
	v_exp_f32_e32 v11, v11
	v_mul_f32_e32 v12, 0x3fb8aa3b, v12
	v_sub_f32_e32 v13, v13, v129
	v_add_f32_e32 v0, v7, v0
	v_exp_f32_e32 v12, v12
	v_mul_f32_e32 v13, 0x3fb8aa3b, v13
	v_sub_f32_e32 v14, v14, v129
	v_add_f32_e32 v0, v8, v0
	v_exp_f32_e32 v13, v13
	v_mul_f32_e32 v14, 0x3fb8aa3b, v14
	v_sub_f32_e32 v15, v15, v129
	v_add_f32_e32 v0, v9, v0
	v_exp_f32_e32 v14, v14
	v_mul_f32_e32 v15, 0x3fb8aa3b, v15
	v_add_f32_e32 v0, v10, v0
	v_sub_f32_e32 v1, v48, v129
	v_exp_f32_e32 v15, v15
	v_cvt_pk_bf16_f32 v25, v2, v3
	v_add_f32_e32 v0, v11, v0
	v_mul_f32_e32 v1, 0x3fb8aa3b, v1
	v_sub_f32_e32 v2, v49, v129
	v_add_f32_e32 v0, v12, v0
	v_exp_f32_e32 v1, v1
	v_mul_f32_e32 v2, 0x3fb8aa3b, v2
	v_sub_f32_e32 v3, v50, v129
	v_cvt_pk_bf16_f32 v21, v26, v27
	v_cvt_pk_bf16_f32 v26, v4, v5
	v_add_f32_e32 v0, v13, v0
	v_exp_f32_e32 v2, v2
	v_mul_f32_e32 v3, 0x3fb8aa3b, v3
	v_sub_f32_e32 v4, v51, v129
	v_add_f32_e32 v0, v14, v0
	v_exp_f32_e32 v3, v3
; __device__ __forceinline__ unsigned pk2(float lo, float hi) { return pg8::cvt_pk_bf16(lo, hi); }
; __device__ __forceinline__ void xattn_core(unsigned char* ws, LAS unsigned char* lds, int b, int hd, int qb, int tid, const bf16x8 (&qf)[16]) {
;     ...
;     float sum = 0.f; bf16x8 pf[8][2];
; #pragma unroll
;     for (int mt = 0; mt < 8; ++mt) {
;         float e[16];
; #pragma unroll
;         for (int r = 0; r < 16; ++r) { e[r] = __expf(sacc[mt][r] - mx); sum += e[r]; }
; #pragma unroll
;         for (int s = 0; s < 2; ++s) { v4u w; w.x = pk2(e[8 * s], e[8 * s + 1]); w.y = pk2(e[8 * s + 2], e[8 * s + 3]); w.z = pk2(e[8 * s + 4], e[8 * s + 5]); w.w = pk2(e[8 * s + 6], e[8 * s + 7]); pf[mt][s] = __builtin_bit_cast(bf16x8, w); }
;     }
	v_mul_f32_e32 v4, 0x3fb8aa3b, v4
	v_sub_f32_e32 v5, v52, v129
	v_cvt_pk_bf16_f32 v27, v6, v7
	v_add_f32_e32 v0, v15, v0
	v_exp_f32_e32 v4, v4
	v_mul_f32_e32 v5, 0x3fb8aa3b, v5
	v_sub_f32_e32 v6, v53, v129
	v_exp_f32_e32 v5, v5
	v_mul_f32_e32 v6, 0x3fb8aa3b, v6
	v_sub_f32_e32 v7, v54, v129
	v_add_f32_e32 v0, v1, v0
	v_cvt_pk_bf16_f32 v22, v28, v29
	v_cvt_pk_bf16_f32 v28, v8, v9
	v_exp_f32_e32 v6, v6
	v_mul_f32_e32 v7, 0x3fb8aa3b, v7
	v_sub_f32_e32 v8, v55, v129
	v_add_f32_e32 v0, v2, v0
	v_exp_f32_e32 v7, v7
	v_mul_f32_e32 v8, 0x3fb8aa3b, v8
	v_sub_f32_e32 v9, v56, v129
	v_add_f32_e32 v0, v3, v0
	v_cvt_pk_bf16_f32 v29, v10, v11
	v_exp_f32_e32 v8, v8
	v_mul_f32_e32 v9, 0x3fb8aa3b, v9
	v_sub_f32_e32 v10, v57, v129
	v_add_f32_e32 v0, v4, v0
	v_exp_f32_e32 v9, v9
	v_mul_f32_e32 v10, 0x3fb8aa3b, v10
	v_sub_f32_e32 v11, v58, v129
	v_add_f32_e32 v0, v5, v0
	v_cvt_pk_bf16_f32 v23, v30, v31
	v_cvt_pk_bf16_f32 v30, v12, v13
	v_exp_f32_e32 v10, v10
	v_mul_f32_e32 v11, 0x3fb8aa3b, v11
	v_sub_f32_e32 v12, v59, v129
	v_add_f32_e32 v0, v6, v0
	v_exp_f32_e32 v11, v11
	v_mul_f32_e32 v12, 0x3fb8aa3b, v12
	v_sub_f32_e32 v13, v60, v129
	v_add_f32_e32 v0, v7, v0
	v_cvt_pk_bf16_f32 v31, v14, v15
	v_exp_f32_e32 v12, v12
	v_mul_f32_e32 v13, 0x3fb8aa3b, v13
	v_sub_f32_e32 v14, v61, v129
	v_add_f32_e32 v0, v8, v0
	v_exp_f32_e32 v13, v13
	v_mul_f32_e32 v14, 0x3fb8aa3b, v14
	v_sub_f32_e32 v15, v62, v129
	v_sub_f32_e32 v40, v63, v129
	v_add_f32_e32 v0, v9, v0
	v_exp_f32_e32 v14, v14
	v_mul_f32_e32 v15, 0x3fb8aa3b, v15
	v_mul_f32_e32 v40, 0x3fb8aa3b, v40
	v_add_f32_e32 v0, v10, v0
	v_exp_f32_e32 v15, v15
	v_exp_f32_e32 v48, v40
	v_cvt_pk_bf16_f32 v40, v1, v2
	v_add_f32_e32 v0, v11, v0
	v_sub_f32_e32 v1, v80, v129
	v_add_f32_e32 v0, v12, v0
	v_mul_f32_e32 v1, 0x3fb8aa3b, v1
	v_sub_f32_e32 v2, v81, v129
	v_cvt_pk_bf16_f32 v16, v41, v42
	v_cvt_pk_bf16_f32 v41, v3, v4
	v_add_f32_e32 v0, v13, v0
	v_exp_f32_e32 v1, v1
	v_mul_f32_e32 v2, 0x3fb8aa3b, v2
	v_sub_f32_e32 v3, v82, v129
	v_add_f32_e32 v0, v14, v0
	v_exp_f32_e32 v2, v2
	v_mul_f32_e32 v3, 0x3fb8aa3b, v3
	v_sub_f32_e32 v4, v83, v129
	v_cvt_pk_bf16_f32 v42, v5, v6
	v_add_f32_e32 v0, v15, v0
	v_exp_f32_e32 v3, v3
	v_mul_f32_e32 v4, 0x3fb8aa3b, v4
	v_sub_f32_e32 v5, v84, v129
	v_add_f32_e32 v0, v48, v0
	v_exp_f32_e32 v4, v4
	v_mul_f32_e32 v5, 0x3fb8aa3b, v5
	v_sub_f32_e32 v6, v85, v129
	v_cvt_pk_bf16_f32 v17, v43, v44
	v_cvt_pk_bf16_f32 v43, v7, v8
	v_exp_f32_e32 v5, v5
	v_mul_f32_e32 v6, 0x3fb8aa3b, v6
	v_sub_f32_e32 v7, v86, v129
	v_add_f32_e32 v0, v1, v0
	v_exp_f32_e32 v6, v6
	v_mul_f32_e32 v7, 0x3fb8aa3b, v7
	v_sub_f32_e32 v8, v87, v129
	v_add_f32_e32 v0, v2, v0
	v_cvt_pk_bf16_f32 v44, v9, v10
	v_exp_f32_e32 v7, v7
	v_mul_f32_e32 v8, 0x3fb8aa3b, v8
	v_sub_f32_e32 v9, v88, v129
	v_add_f32_e32 v0, v3, v0
	v_exp_f32_e32 v8, v8
	v_mul_f32_e32 v9, 0x3fb8aa3b, v9
	v_sub_f32_e32 v10, v89, v129
	v_add_f32_e32 v0, v4, v0
	v_cvt_pk_bf16_f32 v18, v45, v46
	v_cvt_pk_bf16_f32 v45, v11, v12
	v_exp_f32_e32 v9, v9
	v_mul_f32_e32 v10, 0x3fb8aa3b, v10
	v_sub_f32_e32 v11, v90, v129
	v_add_f32_e32 v0, v5, v0
	v_exp_f32_e32 v10, v10
	v_mul_f32_e32 v11, 0x3fb8aa3b, v11
	v_sub_f32_e32 v12, v91, v129
	v_add_f32_e32 v0, v6, v0
	v_cvt_pk_bf16_f32 v46, v13, v14
	v_exp_f32_e32 v11, v11
	v_mul_f32_e32 v12, 0x3fb8aa3b, v12
	v_sub_f32_e32 v13, v92, v129
	v_add_f32_e32 v0, v7, v0
	v_exp_f32_e32 v12, v12
	v_mul_f32_e32 v13, 0x3fb8aa3b, v13
	v_sub_f32_e32 v14, v93, v129
	v_add_f32_e32 v0, v8, v0
	v_cvt_pk_bf16_f32 v19, v47, v104
	v_cvt_pk_bf16_f32 v47, v15, v48
	v_exp_f32_e32 v13, v13
	v_mul_f32_e32 v14, 0x3fb8aa3b, v14
	v_sub_f32_e32 v15, v94, v129
	v_sub_f32_e32 v48, v95, v129
	v_add_f32_e32 v0, v9, v0
	v_exp_f32_e32 v14, v14
	v_mul_f32_e32 v15, 0x3fb8aa3b, v15
	v_mul_f32_e32 v48, 0x3fb8aa3b, v48
	v_add_f32_e32 v0, v10, v0
	v_exp_f32_e32 v15, v15
	v_exp_f32_e32 v56, v48
	v_cvt_pk_bf16_f32 v48, v1, v2
	v_add_f32_e32 v0, v11, v0
	v_sub_f32_e32 v1, v64, v129
	v_add_f32_e32 v0, v12, v0
	v_mul_f32_e32 v1, 0x3fb8aa3b, v1
	v_sub_f32_e32 v2, v65, v129
	v_cvt_pk_bf16_f32 v49, v3, v4
	v_add_f32_e32 v0, v13, v0
	v_exp_f32_e32 v1, v1
	v_mul_f32_e32 v2, 0x3fb8aa3b, v2
	v_sub_f32_e32 v3, v66, v129
	v_add_f32_e32 v0, v14, v0
	v_exp_f32_e32 v2, v2
	v_mul_f32_e32 v3, 0x3fb8aa3b, v3
	v_sub_f32_e32 v4, v67, v129
	v_cvt_pk_bf16_f32 v50, v5, v6
	v_add_f32_e32 v0, v15, v0
	v_exp_f32_e32 v3, v3
	v_mul_f32_e32 v4, 0x3fb8aa3b, v4
	v_sub_f32_e32 v5, v68, v129
	v_add_f32_e32 v0, v56, v0
	v_exp_f32_e32 v4, v4
	v_mul_f32_e32 v5, 0x3fb8aa3b, v5
	v_sub_f32_e32 v6, v69, v129
	v_cvt_pk_bf16_f32 v51, v7, v8
	v_exp_f32_e32 v5, v5
	v_mul_f32_e32 v6, 0x3fb8aa3b, v6
	v_sub_f32_e32 v7, v70, v129
	v_add_f32_e32 v0, v1, v0
	v_exp_f32_e32 v6, v6
	v_mul_f32_e32 v7, 0x3fb8aa3b, v7
; __device__ __forceinline__ unsigned pk2(float lo, float hi) { return pg8::cvt_pk_bf16(lo, hi); }
; __device__ __forceinline__ void xattn_core(unsigned char* ws, LAS unsigned char* lds, int b, int hd, int qb, int tid, const bf16x8 (&qf)[16]) {
;     ...
;     float sum = 0.f; bf16x8 pf[8][2];
; #pragma unroll
;     for (int mt = 0; mt < 8; ++mt) {
;         float e[16];
; #pragma unroll
;         for (int r = 0; r < 16; ++r) { e[r] = __expf(sacc[mt][r] - mx); sum += e[r]; }
; #pragma unroll
;         for (int s = 0; s < 2; ++s) { v4u w; w.x = pk2(e[8 * s], e[8 * s + 1]); w.y = pk2(e[8 * s + 2], e[8 * s + 3]); w.z = pk2(e[8 * s + 4], e[8 * s + 5]); w.w = pk2(e[8 * s + 6], e[8 * s + 7]); pf[mt][s] = __builtin_bit_cast(bf16x8, w); }
;     }
;     sum += __shfl_xor(sum, 32);
;     const float inv = 1.f / sum;
;     __syncthreads();
;     bf16* op = (bf16*)(ws + WS_O) + (size_t)(q0 + r32) * 1024 + hd * 256 + 4 * hh;
	v_sub_f32_e32 v8, v71, v129
	v_add_f32_e32 v0, v2, v0
	v_cvt_pk_bf16_f32 v52, v9, v10
	v_exp_f32_e32 v7, v7
	v_mul_f32_e32 v8, 0x3fb8aa3b, v8
	v_sub_f32_e32 v9, v72, v129
	v_add_f32_e32 v0, v3, v0
	v_exp_f32_e32 v8, v8
	v_mul_f32_e32 v9, 0x3fb8aa3b, v9
	v_sub_f32_e32 v10, v73, v129
	v_add_f32_e32 v0, v4, v0
	v_cvt_pk_bf16_f32 v53, v11, v12
	v_exp_f32_e32 v9, v9
	v_mul_f32_e32 v10, 0x3fb8aa3b, v10
	v_sub_f32_e32 v11, v74, v129
	v_add_f32_e32 v0, v5, v0
	v_exp_f32_e32 v10, v10
	v_mul_f32_e32 v11, 0x3fb8aa3b, v11
	v_sub_f32_e32 v12, v75, v129
	v_add_f32_e32 v0, v6, v0
	v_cvt_pk_bf16_f32 v54, v13, v14
	v_exp_f32_e32 v11, v11
	v_mul_f32_e32 v12, 0x3fb8aa3b, v12
	v_sub_f32_e32 v13, v76, v129
	v_add_f32_e32 v0, v7, v0
	v_exp_f32_e32 v12, v12
	v_mul_f32_e32 v13, 0x3fb8aa3b, v13
	v_sub_f32_e32 v14, v77, v129
	v_add_f32_e32 v0, v8, v0
	v_cvt_pk_bf16_f32 v55, v15, v56
	v_exp_f32_e32 v13, v13
	v_mul_f32_e32 v14, 0x3fb8aa3b, v14
	v_sub_f32_e32 v15, v78, v129
	v_sub_f32_e32 v56, v79, v129
	v_add_f32_e32 v0, v9, v0
	v_exp_f32_e32 v14, v14
	v_mul_f32_e32 v15, 0x3fb8aa3b, v15
	v_mul_f32_e32 v56, 0x3fb8aa3b, v56
	v_add_f32_e32 v0, v10, v0
	v_exp_f32_e32 v15, v15
	v_exp_f32_e32 v64, v56
	v_cvt_pk_bf16_f32 v56, v1, v2
	v_add_f32_e32 v0, v11, v0
	v_sub_f32_e32 v1, v112, v129
	v_add_f32_e32 v0, v12, v0
	v_mul_f32_e32 v1, 0x3fb8aa3b, v1
	v_sub_f32_e32 v2, v113, v129
	v_cvt_pk_bf16_f32 v57, v3, v4
	v_add_f32_e32 v0, v13, v0
	v_exp_f32_e32 v1, v1
	v_mul_f32_e32 v2, 0x3fb8aa3b, v2
	v_sub_f32_e32 v3, v114, v129
	v_add_f32_e32 v0, v14, v0
	v_exp_f32_e32 v2, v2
	v_mul_f32_e32 v3, 0x3fb8aa3b, v3
	v_sub_f32_e32 v4, v115, v129
	v_cvt_pk_bf16_f32 v58, v5, v6
	v_add_f32_e32 v0, v15, v0
	v_exp_f32_e32 v3, v3
	v_mul_f32_e32 v4, 0x3fb8aa3b, v4
	v_sub_f32_e32 v5, v116, v129
	v_add_f32_e32 v0, v64, v0
	v_exp_f32_e32 v4, v4
	v_mul_f32_e32 v5, 0x3fb8aa3b, v5
	v_sub_f32_e32 v6, v117, v129
	v_cvt_pk_bf16_f32 v59, v7, v8
	v_exp_f32_e32 v5, v5
	v_mul_f32_e32 v6, 0x3fb8aa3b, v6
	v_sub_f32_e32 v7, v118, v129
	v_add_f32_e32 v0, v1, v0
	v_exp_f32_e32 v6, v6
	v_mul_f32_e32 v7, 0x3fb8aa3b, v7
	v_sub_f32_e32 v8, v119, v129
	v_add_f32_e32 v0, v2, v0
	v_cvt_pk_bf16_f32 v60, v9, v10
	v_exp_f32_e32 v7, v7
	v_mul_f32_e32 v8, 0x3fb8aa3b, v8
	v_sub_f32_e32 v9, v120, v129
	v_add_f32_e32 v0, v3, v0
	v_exp_f32_e32 v8, v8
	v_mul_f32_e32 v9, 0x3fb8aa3b, v9
	v_sub_f32_e32 v10, v121, v129
	v_add_f32_e32 v0, v4, v0
	v_cvt_pk_bf16_f32 v61, v11, v12
	v_exp_f32_e32 v9, v9
	v_mul_f32_e32 v10, 0x3fb8aa3b, v10
	v_sub_f32_e32 v11, v122, v129
	v_add_f32_e32 v0, v5, v0
	v_exp_f32_e32 v10, v10
	v_mul_f32_e32 v11, 0x3fb8aa3b, v11
	v_sub_f32_e32 v12, v123, v129
	v_add_f32_e32 v0, v6, v0
	v_cvt_pk_bf16_f32 v62, v13, v14
	v_exp_f32_e32 v11, v11
	v_mul_f32_e32 v12, 0x3fb8aa3b, v12
	v_sub_f32_e32 v13, v124, v129
	v_add_f32_e32 v0, v7, v0
	v_exp_f32_e32 v12, v12
	v_mul_f32_e32 v13, 0x3fb8aa3b, v13
	v_sub_f32_e32 v14, v125, v129
	v_add_f32_e32 v0, v8, v0
	v_cvt_pk_bf16_f32 v63, v15, v64
	v_exp_f32_e32 v13, v13
	v_mul_f32_e32 v14, 0x3fb8aa3b, v14
	v_sub_f32_e32 v15, v126, v129
	v_add_f32_e32 v0, v9, v0
	v_exp_f32_e32 v14, v14
	v_mul_f32_e32 v15, 0x3fb8aa3b, v15
	v_sub_f32_e32 v64, v127, v129
	v_add_f32_e32 v0, v10, v0
	v_exp_f32_e32 v15, v15
	v_mul_f32_e32 v64, 0x3fb8aa3b, v64
	v_add_f32_e32 v0, v11, v0
	v_exp_f32_e32 v72, v64
	v_add_f32_e32 v0, v12, v0
	v_add_f32_e32 v0, v13, v0
	v_add_f32_e32 v0, v14, v0
	v_add_f32_e32 v0, v15, v0
	v_add_f32_e32 v0, v72, v0
	v_cvt_pk_bf16_f32 v64, v1, v2
	ds_bpermute_b32 v1, v128, v0
	v_cvt_pk_bf16_f32 v65, v3, v4
	v_cvt_pk_bf16_f32 v66, v5, v6
	v_cvt_pk_bf16_f32 v71, v15, v72
	v_cvt_pk_bf16_f32 v97, v132, v133
	s_waitcnt lgkmcnt(0)
	v_add_f32_e32 v0, v0, v1
	v_div_scale_f32 v1, s[14:15], v0, v0, 1.0
	v_rcp_f32_e32 v2, v1
	v_cvt_pk_bf16_f32 v98, v134, v135
	v_cvt_pk_bf16_f32 v99, v136, v137
	v_cvt_pk_bf16_f32 v32, v105, v106
	v_fma_f32 v3, -v1, v2, 1.0
	v_fmac_f32_e32 v2, v3, v2
	v_div_scale_f32 v3, vcc, 1.0, v0, 1.0
	v_mul_f32_e32 v4, v3, v2
	v_fma_f32 v5, -v1, v4, v3
	v_fmac_f32_e32 v4, v5, v2
	v_fma_f32 v1, -v1, v4, v3
	v_div_fmas_f32 v1, v1, v2, v4
	v_div_fixup_f32 v72, v1, v0, 1.0
	v_add_u32_e32 v0, s6, v214
	v_ashrrev_i32_e32 v1, 31, v0
	v_lshlrev_b64 v[0:1], 11, v[0:1]
	v_lshl_add_u64 v[2:3], s[48:49], 0, v[188:189]
	v_lshl_add_u64 v[0:1], v[0:1], 0, s[4:5]
	v_lshl_add_u64 v[0:1], v[2:3], 0, v[0:1]
	s_mov_b64 s[4:5], 0xc000020
	v_cvt_pk_bf16_f32 v33, v107, v108
	v_cvt_pk_bf16_f32 v34, v109, v110
	v_cvt_pk_bf16_f32 v35, v111, v130
	v_cvt_pk_bf16_f32 v67, v7, v8
	v_cvt_pk_bf16_f32 v68, v9, v10
	v_cvt_pk_bf16_f32 v69, v11, v12
	v_cvt_pk_bf16_f32 v70, v13, v14
	v_mov_b32_e32 v73, v72
	v_lshl_add_u64 v[74:75], v[0:1], 0, s[4:5]
	v_lshlrev_b32_e32 v76, 1, v211
	s_mov_b32 s4, 0
